# conversion LDS swizzle + 32 converter WGs skip last static rounds of P_in/GU (dynamic claims extended)
# baseline (speedup 1.0000x reference)
.LBB0_18:
	s_load_dwordx4 s[20:23], s[0:1], 0xa0
	s_mul_i32 s17, s17, s16
	v_lshrrev_b32_e32 v129, 4, v128
	v_or_b32_e32 v131, 4, v129
	v_mov_b32_e32 v133, 0
	s_waitcnt lgkmcnt(0)
	s_add_u32 s10, s22, s2
	s_addc_u32 s3, s23, s3
	s_sub_i32 s2, s14, s17
	s_lshl_b32 s2, s2, 6
	s_lshl_b64 s[4:5], s[8:9], 1
	s_add_u32 s4, s10, s4
	s_mul_hi_i32 s9, s8, s13
	s_mul_i32 s8, s8, s13
	s_addc_u32 s5, s3, s5
	s_lshl_b64 s[8:9], s[8:9], 2
	s_add_u32 s8, s6, s8
	s_addc_u32 s9, s7, s9
	s_ashr_i32 s3, s2, 31
	s_lshl_b64 s[6:7], s[2:3], 2
	s_add_u32 s6, s8, s6
	v_mul_u32_u24_e32 v0, s13, v129
	v_mul_u32_u24_e32 v2, s13, v131
	s_addc_u32 s7, s9, s7
	v_and_b32_e32 v130, 60, v41
	v_lshlrev_b32_e32 v132, 2, v0
	v_lshlrev_b32_e32 v2, 2, v2
	v_mov_b32_e32 v3, v133
	v_lshl_add_u64 v[0:1], s[6:7], 0, v[132:133]
	v_lshlrev_b32_e32 v132, 2, v130
	v_lshl_add_u64 v[2:3], s[6:7], 0, v[2:3]
	v_or_b32_e32 v135, 8, v129
	v_lshl_add_u64 v[4:5], v[2:3], 0, v[132:133]
	v_mul_u32_u24_e32 v2, s13, v135
	v_lshlrev_b32_e32 v2, 2, v2
	v_mov_b32_e32 v3, v133
	v_lshl_add_u64 v[2:3], s[6:7], 0, v[2:3]
	v_or_b32_e32 v137, 12, v129
	v_lshl_add_u64 v[8:9], v[2:3], 0, v[132:133]
	v_mul_u32_u24_e32 v2, s13, v137
	v_lshlrev_b32_e32 v2, 2, v2
	v_mov_b32_e32 v3, v133
	v_lshl_add_u64 v[2:3], s[6:7], 0, v[2:3]
	v_or_b32_e32 v138, 16, v129
	v_lshl_add_u64 v[12:13], v[2:3], 0, v[132:133]
	v_mul_u32_u24_e32 v2, s13, v138
	v_lshlrev_b32_e32 v2, 2, v2
	v_mov_b32_e32 v3, v133
	v_lshl_add_u64 v[2:3], s[6:7], 0, v[2:3]
	v_or_b32_e32 v139, 20, v129
	v_lshl_add_u64 v[16:17], v[2:3], 0, v[132:133]
	v_mul_u32_u24_e32 v2, s13, v139
	v_lshlrev_b32_e32 v2, 2, v2
	v_mov_b32_e32 v3, v133
	v_lshl_add_u64 v[2:3], s[6:7], 0, v[2:3]
	v_or_b32_e32 v140, 24, v129
	v_lshl_add_u64 v[20:21], v[2:3], 0, v[132:133]
	v_mul_u32_u24_e32 v2, s13, v140
	v_lshlrev_b32_e32 v2, 2, v2
	v_mov_b32_e32 v3, v133
	v_lshl_add_u64 v[2:3], s[6:7], 0, v[2:3]
	v_or_b32_e32 v141, 28, v129
	v_lshl_add_u64 v[24:25], v[2:3], 0, v[132:133]
	v_mul_u32_u24_e32 v2, s13, v141
	v_lshlrev_b32_e32 v2, 2, v2
	v_mov_b32_e32 v3, v133
	v_lshl_add_u64 v[2:3], s[6:7], 0, v[2:3]
	v_or_b32_e32 v142, 32, v129
	v_lshl_add_u64 v[28:29], v[2:3], 0, v[132:133]
	v_mul_u32_u24_e32 v2, s13, v142
	v_lshlrev_b32_e32 v2, 2, v2
	v_mov_b32_e32 v3, v133
	v_lshl_add_u64 v[2:3], s[6:7], 0, v[2:3]
	v_or_b32_e32 v143, 36, v129
	v_lshl_add_u64 v[32:33], v[2:3], 0, v[132:133]
	v_mul_u32_u24_e32 v2, s13, v143
	v_lshlrev_b32_e32 v2, 2, v2
	v_mov_b32_e32 v3, v133
	v_lshl_add_u64 v[2:3], s[6:7], 0, v[2:3]
	v_or_b32_e32 v144, 40, v129
	v_lshl_add_u64 v[36:37], v[2:3], 0, v[132:133]
	v_mul_u32_u24_e32 v2, s13, v144
	v_lshlrev_b32_e32 v2, 2, v2
	v_mov_b32_e32 v3, v133
	v_lshl_add_u64 v[2:3], s[6:7], 0, v[2:3]
	v_or_b32_e32 v145, 44, v129
	v_lshl_add_u64 v[42:43], v[2:3], 0, v[132:133]
	v_mul_u32_u24_e32 v2, s13, v145
	v_lshlrev_b32_e32 v2, 2, v2
	v_mov_b32_e32 v3, v133
	v_lshl_add_u64 v[2:3], s[6:7], 0, v[2:3]
	v_or_b32_e32 v146, 48, v129
	v_lshl_add_u64 v[44:45], v[2:3], 0, v[132:133]
	v_mul_u32_u24_e32 v2, s13, v146
	v_lshlrev_b32_e32 v2, 2, v2
	v_mov_b32_e32 v3, v133
	v_or_b32_e32 v147, 52, v129
	v_lshl_add_u64 v[2:3], s[6:7], 0, v[2:3]
	v_lshl_add_u64 v[46:47], v[2:3], 0, v[132:133]
	v_mul_u32_u24_e32 v2, s13, v147
	v_lshlrev_b32_e32 v2, 2, v2
	v_mov_b32_e32 v3, v133
	v_or_b32_e32 v148, 56, v129
	v_lshl_add_u64 v[2:3], s[6:7], 0, v[2:3]
	v_lshl_add_u64 v[56:57], v[2:3], 0, v[132:133]
	v_mul_u32_u24_e32 v2, s13, v148
	v_lshlrev_b32_e32 v2, 2, v2
	v_mov_b32_e32 v3, v133
	v_or_b32_e32 v149, 60, v129
	v_lshl_add_u64 v[2:3], s[6:7], 0, v[2:3]
	v_lshl_add_u64 v[58:59], v[2:3], 0, v[132:133]
	v_mul_u32_u24_e32 v2, s13, v149
	v_lshlrev_b32_e32 v2, 2, v2
	v_mov_b32_e32 v3, v133
	v_lshl_add_u64 v[0:1], v[0:1], 0, v[132:133]
	v_lshl_add_u64 v[2:3], s[6:7], 0, v[2:3]
	v_lshl_add_u64 v[60:61], v[2:3], 0, v[132:133]
	global_load_dwordx4 v[0:3], v[0:1], off nt
	s_nop 0
	global_load_dwordx4 v[4:7], v[4:5], off nt
	s_nop 0
	global_load_dwordx4 v[8:11], v[8:9], off nt
	s_nop 0
	global_load_dwordx4 v[12:15], v[12:13], off nt
	s_nop 0
	global_load_dwordx4 v[16:19], v[16:17], off nt
	s_nop 0
	global_load_dwordx4 v[20:23], v[20:21], off nt
	s_nop 0
	global_load_dwordx4 v[24:27], v[24:25], off nt
	s_nop 0
	global_load_dwordx4 v[28:31], v[28:29], off nt
	s_nop 0
	global_load_dwordx4 v[32:35], v[32:33], off nt
	s_nop 0
	global_load_dwordx4 v[36:39], v[36:37], off nt
	s_nop 0
	global_load_dwordx4 v[48:51], v[42:43], off nt
	global_load_dwordx4 v[52:55], v[44:45], off nt
	global_load_dwordx4 v[64:67], v[46:47], off nt
	global_load_dwordx4 v[68:71], v[56:57], off nt
	global_load_dwordx4 v[80:83], v[58:59], off nt
	global_load_dwordx4 v[84:87], v[60:61], off nt
	s_mulk_i32 s12, 0x2500
	s_add_i32 s3, s12, 0
	s_movk_i32 s6, 0x90
	v_mov_b32_e32 v42, s3
	v_mad_u32_u24 v42, v130, s6, v42
	v_lshlrev_b32_e32 v43, 1, v129
	v_lshlrev_b32_e32 v44, 1, v131
	v_lshlrev_b32_e32 v45, 1, v135
	v_lshlrev_b32_e32 v46, 1, v137
	v_lshlrev_b32_e32 v47, 1, v138
	v_lshlrev_b32_e32 v56, 1, v139
	v_lshlrev_b32_e32 v57, 1, v140
	v_lshlrev_b32_e32 v58, 1, v141
	v_lshlrev_b32_e32 v59, 1, v142
	v_lshlrev_b32_e32 v60, 1, v143
	v_lshlrev_b32_e32 v61, 1, v144
	v_lshlrev_b32_e32 v62, 1, v145
	v_lshlrev_b32_e32 v63, 1, v146
	v_lshlrev_b32_e32 v72, 1, v147
	v_lshlrev_b32_e32 v73, 1, v148
	v_lshlrev_b32_e32 v74, 1, v149
	v_lshrrev_b32_e32 v150, 3, v128
	v_and_b32_e32 v40, 7, v40
	v_lshl_add_u32 v75, v40, 4, s3
	v_lshlrev_b32_e32 v45, 4, v40
	v_add_u32_e32 v43, v42, v43
	v_add_u32_e32 v44, v42, v44
	v_add_u32_e32 v151, v43, v45
	v_add_u32_e32 v152, v44, v45
	v_xor_b32_e32 v46, 16, v45
	v_add_u32_e32 v153, v43, v46
	v_add_u32_e32 v154, v44, v46
	v_xor_b32_e32 v46, 32, v45
	v_add_u32_e32 v155, v43, v46
	v_add_u32_e32 v156, v44, v46
	v_xor_b32_e32 v46, 48, v45
	v_add_u32_e32 v157, v43, v46
	v_add_u32_e32 v158, v44, v46
	v_xor_b32_e32 v46, 64, v45
	v_add_u32_e32 v159, v43, v46
	v_add_u32_e32 v160, v44, v46
	v_xor_b32_e32 v46, 0x50, v45
	v_add_u32_e32 v161, v43, v46
	v_add_u32_e32 v162, v44, v46
	v_xor_b32_e32 v46, 0x60, v45
	v_add_u32_e32 v163, v43, v46
	v_add_u32_e32 v164, v44, v46
	v_xor_b32_e32 v46, 0x70, v45
	v_add_u32_e32 v165, v43, v46
	v_add_u32_e32 v166, v44, v46
	v_mul_u32_u24_e32 v42, 0x90, v150
	v_add_u32_e32 v47, s3, v42
	v_lshrrev_b32_e32 v56, 2, v150
	v_lshlrev_b32_e32 v56, 4, v56
	v_xor_b32_e32 v56, v56, v45
	v_add_u32_e32 v167, v47, v56
	v_xor_b32_e32 v57, 32, v56
	v_add_u32_e32 v244, v47, v57
	v_xor_b32_e32 v57, 64, v56
	v_add_u32_e32 v245, v47, v57
	v_xor_b32_e32 v57, 0x60, v56
	v_add_u32_e32 v246, v47, v57
	v_add_u32_e32 v168, s3, v41
	s_mov_b32 s6, s2
	s_mov_b64 s[8:9], s[4:5]
	v_lshl_add_u32 v169, v129, 2, s3
	v_lshlrev_b32_e32 v134, 3, v40
	v_or_b32_e32 v170, 8, v150
	v_or_b32_e32 v171, 16, v150
	v_or_b32_e32 v172, 24, v150
	v_or_b32_e32 v173, 32, v150
	v_or_b32_e32 v174, 40, v150
	v_or_b32_e32 v175, 48, v150
	v_or_b32_e32 v176, 56, v150
	v_mov_b32_e32 v177, 1.0
	s_branch .LBB0_23

.LBB0_21:
	ds_write_b32 v168, v177 offset:9216
	s_waitcnt lgkmcnt(0)
	ds_read_b32 v178, v169 offset:9216
	v_or_b32_e32 v182, s6, v150
	v_ashrrev_i32_e32 v183, 31, v182
	v_lshlrev_b64 v[182:183], 13, v[182:183]
	v_lshl_add_u64 v[182:183], s[8:9], 0, v[182:183]
	s_waitcnt lgkmcnt(0)
	v_mul_f32_e32 v179, v44, v178
	v_mul_f32_e32 v180, v45, v178
	v_mul_f32_e32 v181, v46, v178
	v_mul_f32_e32 v178, v47, v178
	v_cvt_pk_bf16_f32 v179, v179, v180
	v_cvt_pk_bf16_f32 v178, v181, v178
	ds_read_b32 v180, v169 offset:9232
	ds_write_b16 v151, v179
	ds_write_b16_d16_hi v151, v179 offset:144
	ds_write_b16 v151, v178 offset:288
	ds_write_b16_d16_hi v151, v178 offset:432
	v_lshl_add_u64 v[186:187], v[182:183], 0, v[132:133]
	s_waitcnt lgkmcnt(4)
	v_mul_f32_e32 v178, v40, v180
	v_mul_f32_e32 v179, v41, v180
	v_cvt_pk_bf16_f32 v178, v178, v179
	v_mul_f32_e32 v179, v42, v180
	v_mul_f32_e32 v180, v43, v180
	v_cvt_pk_bf16_f32 v179, v179, v180
	ds_read_b32 v180, v169 offset:9248
	ds_write_b16 v152, v178
	ds_write_b16_d16_hi v152, v178 offset:144
	ds_write_b16 v152, v179 offset:288
	ds_write_b16_d16_hi v152, v179 offset:432
	s_waitcnt lgkmcnt(4)
	v_mul_f32_e32 v178, v60, v180
	v_mul_f32_e32 v179, v61, v180
	v_cvt_pk_bf16_f32 v178, v178, v179
	v_mul_f32_e32 v179, v62, v180
	v_mul_f32_e32 v180, v63, v180
	v_cvt_pk_bf16_f32 v179, v179, v180
	ds_read_b32 v180, v169 offset:9264
	ds_write_b16 v153, v178
	ds_write_b16_d16_hi v153, v178 offset:144
	ds_write_b16 v153, v179 offset:288
	ds_write_b16_d16_hi v153, v179 offset:432
	s_waitcnt lgkmcnt(4)
	v_mul_f32_e32 v178, v56, v180
	v_mul_f32_e32 v179, v57, v180
	v_cvt_pk_bf16_f32 v178, v178, v179
	v_mul_f32_e32 v179, v58, v180
	v_mul_f32_e32 v180, v59, v180
	v_cvt_pk_bf16_f32 v179, v179, v180
	ds_read_b32 v180, v169 offset:9280
	ds_write_b16 v154, v178
	ds_write_b16_d16_hi v154, v178 offset:144
	ds_write_b16 v154, v179 offset:288
	ds_write_b16_d16_hi v154, v179 offset:432
	s_waitcnt lgkmcnt(4)
	v_mul_f32_e32 v178, v76, v180
	v_mul_f32_e32 v179, v77, v180
	v_cvt_pk_bf16_f32 v178, v178, v179
	v_mul_f32_e32 v179, v78, v180
	v_mul_f32_e32 v180, v79, v180
	v_cvt_pk_bf16_f32 v179, v179, v180
	ds_read_b32 v180, v169 offset:9296
	ds_write_b16 v155, v178
	ds_write_b16_d16_hi v155, v178 offset:144
	ds_write_b16 v155, v179 offset:288
	ds_write_b16_d16_hi v155, v179 offset:432
	s_waitcnt lgkmcnt(4)
	v_mul_f32_e32 v178, v72, v180
	v_mul_f32_e32 v179, v73, v180
	v_cvt_pk_bf16_f32 v178, v178, v179
	v_mul_f32_e32 v179, v74, v180
	v_mul_f32_e32 v180, v75, v180
	v_cvt_pk_bf16_f32 v179, v179, v180
	ds_read_b32 v180, v169 offset:9312
	ds_write_b16 v156, v178
	ds_write_b16_d16_hi v156, v178 offset:144
	ds_write_b16 v156, v179 offset:288
	ds_write_b16_d16_hi v156, v179 offset:432
	s_waitcnt lgkmcnt(4)
	v_mul_f32_e32 v178, v92, v180
	v_mul_f32_e32 v179, v93, v180
	v_cvt_pk_bf16_f32 v178, v178, v179
	v_mul_f32_e32 v179, v94, v180
	v_mul_f32_e32 v180, v95, v180
	v_cvt_pk_bf16_f32 v179, v179, v180
	ds_read_b32 v180, v169 offset:9328
	ds_write_b16 v157, v178
	ds_write_b16_d16_hi v157, v178 offset:144
	ds_write_b16 v157, v179 offset:288
	ds_write_b16_d16_hi v157, v179 offset:432
	s_waitcnt lgkmcnt(4)
	v_mul_f32_e32 v178, v88, v180
	v_mul_f32_e32 v179, v89, v180
	v_cvt_pk_bf16_f32 v178, v178, v179
	v_mul_f32_e32 v179, v90, v180
	v_mul_f32_e32 v180, v91, v180
	v_cvt_pk_bf16_f32 v179, v179, v180
	ds_read_b32 v180, v169 offset:9344
	ds_write_b16 v158, v178
	ds_write_b16_d16_hi v158, v178 offset:144
	ds_write_b16 v158, v179 offset:288
	ds_write_b16_d16_hi v158, v179 offset:432
	s_waitcnt lgkmcnt(4)
	v_mul_f32_e32 v178, v100, v180
	v_mul_f32_e32 v179, v101, v180
	v_cvt_pk_bf16_f32 v178, v178, v179
	v_mul_f32_e32 v179, v102, v180
	v_mul_f32_e32 v180, v103, v180
	v_cvt_pk_bf16_f32 v179, v179, v180
	ds_read_b32 v180, v169 offset:9360
	ds_write_b16 v159, v178
	ds_write_b16_d16_hi v159, v178 offset:144
	ds_write_b16 v159, v179 offset:288
	ds_write_b16_d16_hi v159, v179 offset:432
	s_waitcnt lgkmcnt(4)
	v_mul_f32_e32 v178, v96, v180
	v_mul_f32_e32 v179, v97, v180
	v_cvt_pk_bf16_f32 v178, v178, v179
	v_mul_f32_e32 v179, v98, v180
	v_mul_f32_e32 v180, v99, v180
	v_cvt_pk_bf16_f32 v179, v179, v180
	ds_read_b32 v180, v169 offset:9376
	ds_write_b16 v160, v178
	ds_write_b16_d16_hi v160, v178 offset:144
	ds_write_b16 v160, v179 offset:288
	ds_write_b16_d16_hi v160, v179 offset:432
	s_waitcnt lgkmcnt(4)
	v_mul_f32_e32 v178, v108, v180
	v_mul_f32_e32 v179, v109, v180
	v_cvt_pk_bf16_f32 v178, v178, v179
	v_mul_f32_e32 v179, v110, v180
	v_mul_f32_e32 v180, v111, v180
	v_cvt_pk_bf16_f32 v179, v179, v180
	ds_read_b32 v180, v169 offset:9392
	ds_write_b16 v161, v178
	ds_write_b16_d16_hi v161, v178 offset:144
	ds_write_b16 v161, v179 offset:288
	ds_write_b16_d16_hi v161, v179 offset:432
	s_waitcnt lgkmcnt(4)
	v_mul_f32_e32 v178, v104, v180
	v_mul_f32_e32 v179, v105, v180
	v_cvt_pk_bf16_f32 v178, v178, v179
	v_mul_f32_e32 v179, v106, v180
	v_mul_f32_e32 v180, v107, v180
	v_cvt_pk_bf16_f32 v179, v179, v180
	ds_read_b32 v180, v169 offset:9408
	ds_write_b16 v162, v178
	ds_write_b16_d16_hi v162, v178 offset:144
	ds_write_b16 v162, v179 offset:288
	ds_write_b16_d16_hi v162, v179 offset:432
	s_waitcnt lgkmcnt(4)
	v_mul_f32_e32 v178, v116, v180
	v_mul_f32_e32 v179, v117, v180
	v_cvt_pk_bf16_f32 v178, v178, v179
	v_mul_f32_e32 v179, v118, v180
	v_mul_f32_e32 v180, v119, v180
	v_cvt_pk_bf16_f32 v179, v179, v180
	ds_read_b32 v180, v169 offset:9424
	ds_write_b16 v163, v178
	ds_write_b16_d16_hi v163, v178 offset:144
	ds_write_b16 v163, v179 offset:288
	ds_write_b16_d16_hi v163, v179 offset:432
	s_waitcnt lgkmcnt(4)
	v_mul_f32_e32 v178, v112, v180
	v_mul_f32_e32 v179, v113, v180
	v_cvt_pk_bf16_f32 v178, v178, v179
	v_mul_f32_e32 v179, v114, v180
	v_mul_f32_e32 v180, v115, v180
	v_cvt_pk_bf16_f32 v179, v179, v180
	ds_read_b32 v180, v169 offset:9440
	ds_write_b16 v164, v178
	ds_write_b16_d16_hi v164, v178 offset:144
	ds_write_b16 v164, v179 offset:288
	ds_write_b16_d16_hi v164, v179 offset:432
	s_waitcnt lgkmcnt(4)
	v_mul_f32_e32 v178, v124, v180
	v_mul_f32_e32 v179, v125, v180
	v_cvt_pk_bf16_f32 v178, v178, v179
	v_mul_f32_e32 v179, v126, v180
	v_mul_f32_e32 v180, v127, v180
	v_cvt_pk_bf16_f32 v179, v179, v180
	ds_read_b32 v180, v169 offset:9456
	ds_write_b16 v165, v178
	ds_write_b16_d16_hi v165, v178 offset:144
	ds_write_b16 v165, v179 offset:288
	ds_write_b16_d16_hi v165, v179 offset:432
	s_waitcnt lgkmcnt(4)
	v_mul_f32_e32 v178, v120, v180
	v_mul_f32_e32 v179, v121, v180
	v_cvt_pk_bf16_f32 v178, v178, v179
	v_mul_f32_e32 v179, v122, v180
	v_mul_f32_e32 v180, v123, v180
	v_cvt_pk_bf16_f32 v179, v179, v180
	ds_write_b16 v166, v178
	ds_write_b16_d16_hi v166, v178 offset:144
	ds_write_b16 v166, v179 offset:288
	ds_write_b16_d16_hi v166, v179 offset:432
	s_waitcnt lgkmcnt(0)
	ds_read_b128 v[178:181], v167
	ds_read_b128 v[182:185], v244 offset:1152
	s_waitcnt lgkmcnt(1)
	global_store_dwordx4 v[186:187], v[178:181], off
	s_nop 1
	v_or_b32_e32 v178, s6, v170
	v_ashrrev_i32_e32 v179, 31, v178
	v_lshlrev_b64 v[178:179], 13, v[178:179]
	v_lshl_add_u64 v[178:179], s[8:9], 0, v[178:179]
	v_lshl_add_u64 v[178:179], v[178:179], 0, v[132:133]
	s_waitcnt lgkmcnt(0)
	global_store_dwordx4 v[178:179], v[182:185], off
	ds_read_b128 v[178:181], v245 offset:2304
	s_nop 0
	v_or_b32_e32 v182, s6, v171
	v_ashrrev_i32_e32 v183, 31, v182
	v_lshlrev_b64 v[182:183], 13, v[182:183]
	v_lshl_add_u64 v[182:183], s[8:9], 0, v[182:183]
	v_lshl_add_u64 v[186:187], v[182:183], 0, v[132:133]
	ds_read_b128 v[182:185], v246 offset:3456
	s_waitcnt lgkmcnt(1)
	global_store_dwordx4 v[186:187], v[178:181], off
	s_nop 1
	v_or_b32_e32 v178, s6, v172
	v_ashrrev_i32_e32 v179, 31, v178
	v_lshlrev_b64 v[178:179], 13, v[178:179]
	v_lshl_add_u64 v[178:179], s[8:9], 0, v[178:179]
	v_lshl_add_u64 v[178:179], v[178:179], 0, v[132:133]
	s_waitcnt lgkmcnt(0)
	global_store_dwordx4 v[178:179], v[182:185], off
	ds_read_b128 v[178:181], v167 offset:4608
	s_nop 0
	v_or_b32_e32 v182, s6, v173
	v_ashrrev_i32_e32 v183, 31, v182
	v_lshlrev_b64 v[182:183], 13, v[182:183]
	v_lshl_add_u64 v[182:183], s[8:9], 0, v[182:183]
	v_lshl_add_u64 v[186:187], v[182:183], 0, v[132:133]
	ds_read_b128 v[182:185], v244 offset:5760
	s_waitcnt lgkmcnt(1)
	global_store_dwordx4 v[186:187], v[178:181], off
	s_nop 1
	v_or_b32_e32 v178, s6, v174
	v_ashrrev_i32_e32 v179, 31, v178
	v_lshlrev_b64 v[178:179], 13, v[178:179]
	v_lshl_add_u64 v[178:179], s[8:9], 0, v[178:179]
	v_lshl_add_u64 v[178:179], v[178:179], 0, v[132:133]
	s_waitcnt lgkmcnt(0)
	global_store_dwordx4 v[178:179], v[182:185], off
	ds_read_b128 v[178:181], v245 offset:6912
	s_nop 0
	v_or_b32_e32 v182, s6, v175
	v_ashrrev_i32_e32 v183, 31, v182
	v_lshlrev_b64 v[182:183], 13, v[182:183]
	v_lshl_add_u64 v[182:183], s[8:9], 0, v[182:183]
	v_lshl_add_u64 v[186:187], v[182:183], 0, v[132:133]
	ds_read_b128 v[182:185], v246 offset:8064
	s_waitcnt lgkmcnt(1)
	global_store_dwordx4 v[186:187], v[178:181], off
	s_nop 1
	v_or_b32_e32 v178, s6, v176
	v_ashrrev_i32_e32 v179, 31, v178
	v_lshlrev_b64 v[178:179], 13, v[178:179]
	v_lshl_add_u64 v[178:179], s[8:9], 0, v[178:179]
	v_lshl_add_u64 v[178:179], v[178:179], 0, v[132:133]
	s_waitcnt lgkmcnt(0)
	global_store_dwordx4 v[178:179], v[182:185], off
	s_waitcnt lgkmcnt(0)

.LBB0_31:
	s_waitcnt vmcnt(16)
	ds_write_b32 v168, v136 offset:9216
	s_waitcnt lgkmcnt(0)
	ds_read_b32 v132, v169 offset:9216
	v_or_b32_e32 v182, s2, v150
	v_ashrrev_i32_e32 v183, 31, v182
	v_lshlrev_b64 v[182:183], 13, v[182:183]
	v_lshl_add_u64 v[182:183], s[4:5], 0, v[182:183]
	s_waitcnt vmcnt(15) lgkmcnt(0)
	v_mul_f32_e32 v178, v0, v132
	v_mul_f32_e32 v179, v1, v132
	v_mul_f32_e32 v180, v2, v132
	v_mul_f32_e32 v132, v3, v132
	v_cvt_pk_bf16_f32 v178, v178, v179
	v_cvt_pk_bf16_f32 v132, v180, v132
	ds_read_b32 v179, v169 offset:9232
	ds_write_b16 v151, v178
	ds_write_b16_d16_hi v151, v178 offset:144
	ds_write_b16 v151, v132 offset:288
	ds_write_b16_d16_hi v151, v132 offset:432
	s_andn2_b64 vcc, exec, s[10:11]
	s_mov_b64 s[10:11], -1
	s_waitcnt vmcnt(14) lgkmcnt(4)
	v_mul_f32_e32 v132, v4, v179
	v_mul_f32_e32 v178, v5, v179
	v_cvt_pk_bf16_f32 v132, v132, v178
	v_mul_f32_e32 v178, v6, v179
	v_mul_f32_e32 v179, v7, v179
	v_cvt_pk_bf16_f32 v178, v178, v179
	ds_read_b32 v179, v169 offset:9248
	ds_write_b16 v152, v132
	ds_write_b16_d16_hi v152, v132 offset:144
	ds_write_b16 v152, v178 offset:288
	ds_write_b16_d16_hi v152, v178 offset:432
	s_waitcnt vmcnt(13) lgkmcnt(4)
	v_mul_f32_e32 v132, v8, v179
	v_mul_f32_e32 v178, v9, v179
	v_cvt_pk_bf16_f32 v132, v132, v178
	v_mul_f32_e32 v178, v10, v179
	v_mul_f32_e32 v179, v11, v179
	v_cvt_pk_bf16_f32 v178, v178, v179
	ds_read_b32 v179, v169 offset:9264
	ds_write_b16 v153, v132
	ds_write_b16_d16_hi v153, v132 offset:144
	ds_write_b16 v153, v178 offset:288
	ds_write_b16_d16_hi v153, v178 offset:432
	s_waitcnt vmcnt(12) lgkmcnt(4)
	v_mul_f32_e32 v132, v12, v179
	v_mul_f32_e32 v178, v13, v179
	v_cvt_pk_bf16_f32 v132, v132, v178
	v_mul_f32_e32 v178, v14, v179
	v_mul_f32_e32 v179, v15, v179
	v_cvt_pk_bf16_f32 v178, v178, v179
	ds_read_b32 v179, v169 offset:9280
	ds_write_b16 v154, v132
	ds_write_b16_d16_hi v154, v132 offset:144
	ds_write_b16 v154, v178 offset:288
	ds_write_b16_d16_hi v154, v178 offset:432
	s_waitcnt vmcnt(11) lgkmcnt(4)
	v_mul_f32_e32 v132, v16, v179
	v_mul_f32_e32 v178, v17, v179
	v_cvt_pk_bf16_f32 v132, v132, v178
	v_mul_f32_e32 v178, v18, v179
	v_mul_f32_e32 v179, v19, v179
	v_cvt_pk_bf16_f32 v178, v178, v179
	ds_read_b32 v179, v169 offset:9296
	ds_write_b16 v155, v132
	ds_write_b16_d16_hi v155, v132 offset:144
	ds_write_b16 v155, v178 offset:288
	ds_write_b16_d16_hi v155, v178 offset:432
	s_waitcnt vmcnt(10) lgkmcnt(4)
	v_mul_f32_e32 v132, v20, v179
	v_mul_f32_e32 v178, v21, v179
	v_cvt_pk_bf16_f32 v132, v132, v178
	v_mul_f32_e32 v178, v22, v179
	v_mul_f32_e32 v179, v23, v179
	v_cvt_pk_bf16_f32 v178, v178, v179
	ds_read_b32 v179, v169 offset:9312
	ds_write_b16 v156, v132
	ds_write_b16_d16_hi v156, v132 offset:144
	ds_write_b16 v156, v178 offset:288
	ds_write_b16_d16_hi v156, v178 offset:432
	s_waitcnt vmcnt(9) lgkmcnt(4)
	v_mul_f32_e32 v132, v24, v179
	v_mul_f32_e32 v178, v25, v179
	v_cvt_pk_bf16_f32 v132, v132, v178
	v_mul_f32_e32 v178, v26, v179
	v_mul_f32_e32 v179, v27, v179
	v_cvt_pk_bf16_f32 v178, v178, v179
	ds_read_b32 v179, v169 offset:9328
	ds_write_b16 v157, v132
	ds_write_b16_d16_hi v157, v132 offset:144
	ds_write_b16 v157, v178 offset:288
	ds_write_b16_d16_hi v157, v178 offset:432
	s_waitcnt vmcnt(8) lgkmcnt(4)
	v_mul_f32_e32 v132, v28, v179
	v_mul_f32_e32 v178, v29, v179
	v_cvt_pk_bf16_f32 v132, v132, v178
	v_mul_f32_e32 v178, v30, v179
	v_mul_f32_e32 v179, v31, v179
	v_cvt_pk_bf16_f32 v178, v178, v179
	ds_read_b32 v179, v169 offset:9344
	ds_write_b16 v158, v132
	ds_write_b16_d16_hi v158, v132 offset:144
	ds_write_b16 v158, v178 offset:288
	ds_write_b16_d16_hi v158, v178 offset:432
	s_waitcnt vmcnt(7) lgkmcnt(4)
	v_mul_f32_e32 v132, v32, v179
	v_mul_f32_e32 v178, v33, v179
	v_cvt_pk_bf16_f32 v132, v132, v178
	v_mul_f32_e32 v178, v34, v179
	v_mul_f32_e32 v179, v35, v179
	v_cvt_pk_bf16_f32 v178, v178, v179
	ds_read_b32 v179, v169 offset:9360
	ds_write_b16 v159, v132
	ds_write_b16_d16_hi v159, v132 offset:144
	ds_write_b16 v159, v178 offset:288
	ds_write_b16_d16_hi v159, v178 offset:432
	s_waitcnt vmcnt(6) lgkmcnt(4)
	v_mul_f32_e32 v132, v36, v179
	v_mul_f32_e32 v178, v37, v179
	v_cvt_pk_bf16_f32 v132, v132, v178
	v_mul_f32_e32 v178, v38, v179
	v_mul_f32_e32 v179, v39, v179
	v_cvt_pk_bf16_f32 v178, v178, v179
	ds_read_b32 v179, v169 offset:9376
	ds_write_b16 v160, v132
	ds_write_b16_d16_hi v160, v132 offset:144
	ds_write_b16 v160, v178 offset:288
	ds_write_b16_d16_hi v160, v178 offset:432
	s_waitcnt vmcnt(5) lgkmcnt(4)
	v_mul_f32_e32 v132, v48, v179
	v_mul_f32_e32 v178, v49, v179
	v_cvt_pk_bf16_f32 v132, v132, v178
	v_mul_f32_e32 v178, v50, v179
	v_mul_f32_e32 v179, v51, v179
	v_cvt_pk_bf16_f32 v178, v178, v179
	ds_read_b32 v179, v169 offset:9392
	ds_write_b16 v161, v132
	ds_write_b16_d16_hi v161, v132 offset:144
	ds_write_b16 v161, v178 offset:288
	ds_write_b16_d16_hi v161, v178 offset:432
	s_waitcnt vmcnt(4) lgkmcnt(4)
	v_mul_f32_e32 v132, v52, v179
	v_mul_f32_e32 v178, v53, v179
	v_cvt_pk_bf16_f32 v132, v132, v178
	v_mul_f32_e32 v178, v54, v179
	v_mul_f32_e32 v179, v55, v179
	v_cvt_pk_bf16_f32 v178, v178, v179
	ds_read_b32 v179, v169 offset:9408
	ds_write_b16 v162, v132
	ds_write_b16_d16_hi v162, v132 offset:144
	ds_write_b16 v162, v178 offset:288
	ds_write_b16_d16_hi v162, v178 offset:432
	s_waitcnt vmcnt(3) lgkmcnt(4)
	v_mul_f32_e32 v132, v64, v179
	v_mul_f32_e32 v178, v65, v179
	v_cvt_pk_bf16_f32 v132, v132, v178
	v_mul_f32_e32 v178, v66, v179
	v_mul_f32_e32 v179, v67, v179
	v_cvt_pk_bf16_f32 v178, v178, v179
	ds_read_b32 v179, v169 offset:9424
	ds_write_b16 v163, v132
	ds_write_b16_d16_hi v163, v132 offset:144
	ds_write_b16 v163, v178 offset:288
	ds_write_b16_d16_hi v163, v178 offset:432
	s_waitcnt vmcnt(2) lgkmcnt(4)
	v_mul_f32_e32 v132, v68, v179
	v_mul_f32_e32 v178, v69, v179
	v_cvt_pk_bf16_f32 v132, v132, v178
	v_mul_f32_e32 v178, v70, v179
	v_mul_f32_e32 v179, v71, v179
	v_cvt_pk_bf16_f32 v178, v178, v179
	ds_read_b32 v179, v169 offset:9440
	ds_write_b16 v164, v132
	ds_write_b16_d16_hi v164, v132 offset:144
	ds_write_b16 v164, v178 offset:288
	ds_write_b16_d16_hi v164, v178 offset:432
	s_waitcnt vmcnt(1) lgkmcnt(4)
	v_mul_f32_e32 v132, v80, v179
	v_mul_f32_e32 v178, v81, v179
	v_cvt_pk_bf16_f32 v132, v132, v178
	v_mul_f32_e32 v178, v82, v179
	v_mul_f32_e32 v179, v83, v179
	v_cvt_pk_bf16_f32 v178, v178, v179
	ds_read_b32 v179, v169 offset:9456
	ds_write_b16 v165, v132
	ds_write_b16_d16_hi v165, v132 offset:144
	ds_write_b16 v165, v178 offset:288
	ds_write_b16_d16_hi v165, v178 offset:432
	s_waitcnt vmcnt(0) lgkmcnt(4)
	v_mul_f32_e32 v132, v84, v179
	v_mul_f32_e32 v178, v85, v179
	v_cvt_pk_bf16_f32 v132, v132, v178
	v_mul_f32_e32 v178, v86, v179
	v_mul_f32_e32 v179, v87, v179
	v_cvt_pk_bf16_f32 v178, v178, v179
	ds_write_b16 v166, v132
	ds_write_b16_d16_hi v166, v132 offset:144
	ds_write_b16 v166, v178 offset:288
	ds_write_b16_d16_hi v166, v178 offset:432
	s_waitcnt lgkmcnt(0)
	ds_read_b128 v[178:181], v167
	v_lshlrev_b32_e32 v132, 1, v134
	v_lshl_add_u64 v[186:187], v[182:183], 0, v[132:133]
	ds_read_b128 v[182:185], v244 offset:1152
	s_waitcnt lgkmcnt(1)
	global_store_dwordx4 v[186:187], v[178:181], off
	s_nop 1
	v_or_b32_e32 v178, s2, v170
	v_ashrrev_i32_e32 v179, 31, v178
	v_lshlrev_b64 v[178:179], 13, v[178:179]
	v_lshl_add_u64 v[178:179], s[4:5], 0, v[178:179]
	v_lshl_add_u64 v[178:179], v[178:179], 0, v[132:133]
	s_waitcnt lgkmcnt(0)
	global_store_dwordx4 v[178:179], v[182:185], off
	ds_read_b128 v[178:181], v245 offset:2304
	s_nop 0
	v_or_b32_e32 v182, s2, v171
	v_ashrrev_i32_e32 v183, 31, v182
	v_lshlrev_b64 v[182:183], 13, v[182:183]
	v_lshl_add_u64 v[182:183], s[4:5], 0, v[182:183]
	v_lshl_add_u64 v[186:187], v[182:183], 0, v[132:133]
	ds_read_b128 v[182:185], v246 offset:3456
	s_waitcnt lgkmcnt(1)
	global_store_dwordx4 v[186:187], v[178:181], off
	s_nop 1
	v_or_b32_e32 v178, s2, v172
	v_ashrrev_i32_e32 v179, 31, v178
	v_lshlrev_b64 v[178:179], 13, v[178:179]
	v_lshl_add_u64 v[178:179], s[4:5], 0, v[178:179]
	v_lshl_add_u64 v[178:179], v[178:179], 0, v[132:133]
	s_waitcnt lgkmcnt(0)
	global_store_dwordx4 v[178:179], v[182:185], off
	ds_read_b128 v[178:181], v167 offset:4608
	s_nop 0
	v_or_b32_e32 v182, s2, v173
	v_ashrrev_i32_e32 v183, 31, v182
	v_lshlrev_b64 v[182:183], 13, v[182:183]
	v_lshl_add_u64 v[182:183], s[4:5], 0, v[182:183]
	v_lshl_add_u64 v[186:187], v[182:183], 0, v[132:133]
	ds_read_b128 v[182:185], v244 offset:5760
	s_waitcnt lgkmcnt(1)
	global_store_dwordx4 v[186:187], v[178:181], off
	s_nop 1
	v_or_b32_e32 v178, s2, v174
	v_ashrrev_i32_e32 v179, 31, v178
	v_lshlrev_b64 v[178:179], 13, v[178:179]
	v_lshl_add_u64 v[178:179], s[4:5], 0, v[178:179]
	v_lshl_add_u64 v[178:179], v[178:179], 0, v[132:133]
	s_waitcnt lgkmcnt(0)
	global_store_dwordx4 v[178:179], v[182:185], off
	ds_read_b128 v[178:181], v245 offset:6912
	s_nop 0
	v_or_b32_e32 v182, s2, v175
	v_ashrrev_i32_e32 v183, 31, v182
	v_lshlrev_b64 v[182:183], 13, v[182:183]
	v_lshl_add_u64 v[182:183], s[4:5], 0, v[182:183]
	v_lshl_add_u64 v[186:187], v[182:183], 0, v[132:133]
	ds_read_b128 v[182:185], v246 offset:8064
	s_waitcnt lgkmcnt(1)
	global_store_dwordx4 v[186:187], v[178:181], off
	s_nop 1
	v_or_b32_e32 v178, s2, v176
	v_ashrrev_i32_e32 v179, 31, v178
	v_lshlrev_b64 v[178:179], 13, v[178:179]
	v_lshl_add_u64 v[178:179], s[4:5], 0, v[178:179]
	v_lshl_add_u64 v[178:179], v[178:179], 0, v[132:133]
	s_waitcnt lgkmcnt(0)
	global_store_dwordx4 v[178:179], v[182:185], off
	s_waitcnt lgkmcnt(0)
	s_cbranch_vccnz .LBB0_22
	s_cmpk_gt_i32 s15, 0x1627
	s_cselect_b64 s[10:11], -1, 0
	s_and_b64 vcc, exec, s[10:11]
	s_cbranch_vccnz .LBB0_21
	s_add_i32 s14, s15, 0x1000
	s_cmpk_lt_i32 s15, 0xa00
	s_cbranch_scc1 .LBB0_35
	s_load_dwordx16 s[36:51], s[0:1], 0x0
	s_addk_i32 s15, 0xf600
	s_mov_b64 s[2:3], 0x3500000
	s_mov_b64 s[4:5], 0
	s_movk_i32 s7, 0x1000
	s_waitcnt lgkmcnt(0)
	s_mov_b64 s[12:13], s[48:49]
	s_branch .LBB0_36

.LBB0_107:
	s_xor_b64 s[0:1], s[0:1], -1
	v_writelane_b32 v254, s0, 11
	s_mov_b32 s9, s87
	v_readlane_b32 s4, v252, 0
	v_writelane_b32 v254, s1, 12
	s_mul_i32 s0, s8, 0x15600000
	s_add_u32 s58, s33, s0
	s_addc_u32 s0, s36, 0
	v_writelane_b32 v254, s0, 13
	s_lshl_b64 s[0:1], s[8:9], 19
	v_readlane_b32 s5, v252, 1
	s_add_u32 s31, s4, s0
	s_addc_u32 s40, s5, s1
	s_lshl_b64 s[2:3], s[8:9], 18
	s_sub_u32 s0, 0, s2
	s_subb_u32 s1, 0, s3
	s_add_u32 s61, s31, s0
	s_addc_u32 s62, s40, s1
	s_lshl_b32 s86, s8, 7
	s_mov_b64 s[38:39], s[2:3]
	s_lshl_b64 s[2:3], s[86:87], 2
	v_readlane_b32 s0, v252, 54
	s_add_u32 s42, s0, s2
	v_readlane_b32 s0, v252, 55
	v_writelane_b32 v254, s2, 14
	s_addc_u32 s43, s0, s3
	v_readlane_b32 s0, v253, 34
	s_mov_b64 s[36:37], s[8:9]
	v_writelane_b32 v254, s3, 15
	s_mov_b32 s63, s0
	s_mov_b32 s79, s87
	s_mov_b32 s78, 3
	s_cmp_eq_u32 s8, 0
	s_cselect_b32 s2, 1, 2
	s_cmp_ge_u32 s0, 0xe0
	s_cselect_b32 s78, s2, 3
	v_readlane_b32 s6, v252, 2
	v_readlane_b32 s7, v252, 3
	v_readlane_b32 s1, v253, 35
	s_branch .LBB0_110

.LBB0_109:
	s_or_b64 exec, exec, s[0:1]
	v_mov_b32_e32 v0, s81
	s_waitcnt vmcnt(0) lgkmcnt(0)
	s_barrier
	ds_read_b32 v0, v0
	s_mov_b32 s78, 1
	s_mov_b32 s79, 3
	s_waitcnt lgkmcnt(0)
	s_barrier
	v_readfirstlane_b32 s63, v0
	s_cmpk_lt_i32 s63, 0x5a
	s_cbranch_scc1 .LBB0_110
	s_sub_i32 s63, s63, 0x5a
	s_cmp_eq_u32 s36, 0
	s_cselect_b32 s0, 64, 32
	s_cmp_lt_i32 s63, s0
	s_cbranch_scc0 .LBB0_309
	s_lshr_b32 s0, s63, 5
	s_sub_i32 s79, 2, s0
	s_and_b32 s63, s63, 31
	s_addk_i32 s63, 0xe0

.LBB0_306:
	s_waitcnt vmcnt(0)
	v_readlane_b32 s90, v255, 59
	v_readlane_b32 s91, v255, 60
	s_mov_b32 s80, 0x20000
	s_movk_i32 s52, 0x90
	v_readlane_b32 s81, v255, 62
	v_readlane_b32 s83, v255, 63
	s_mov_b32 s94, 0xf800000
	s_mov_b32 s95, 0x40000
	s_mov_b32 s96, 0x60000
	s_barrier
	v_readlane_b32 s0, v253, 34
	s_nop 0
	s_cmp_ge_u32 s0, 0xe0
	s_cbranch_scc1 .LBB0_309
	s_and_saveexec_b64 s[0:1], s[90:91]
	s_cbranch_execz .LBB0_109

.LBB0_313:
	s_or_b64 exec, exec, s[2:3]
	v_readlane_b32 s8, v255, 45
	v_readlane_b32 s9, v255, 46
	s_and_b64 s[2:3], s[8:9], exec
	s_mov_b32 s2, 0x12b00
	s_cselect_b32 s61, 0x8000, s2
	s_ashr_i32 s20, s10, 6
	v_and_b32_e32 v130, 63, v0
	s_mul_i32 s2, s20, 0x2500
	s_add_i32 s6, s2, 0
	v_bfe_u32 v133, v0, 4, 2
	v_lshlrev_b32_e32 v2, 2, v130
	s_and_b64 s[2:3], s[8:9], exec
	v_and_b32_e32 v132, 60, v2
	v_or_b32_e32 v135, 4, v133
	v_or_b32_e32 v138, 8, v133
	v_or_b32_e32 v139, 12, v133
	v_or_b32_e32 v140, 16, v133
	v_or_b32_e32 v141, 20, v133
	v_or_b32_e32 v142, 24, v133
	v_or_b32_e32 v143, 28, v133
	v_or_b32_e32 v144, 32, v133
	v_or_b32_e32 v145, 36, v133
	v_or_b32_e32 v146, 40, v133
	v_or_b32_e32 v147, 44, v133
	v_or_b32_e32 v148, 48, v133
	v_or_b32_e32 v149, 52, v133
	v_or_b32_e32 v150, 56, v133
	v_or_b32_e32 v151, 60, v133
	v_add_u32_e32 v152, s6, v2
	v_mov_b32_e32 v2, s6
	v_bfe_u32 v154, v0, 3, 3
	v_and_b32_e32 v0, 7, v0
	s_movk_i32 s2, 0x2628
	v_mad_u32_u24 v2, v132, s52, v2
	v_lshlrev_b32_e32 v3, 1, v133
	v_lshlrev_b32_e32 v4, 1, v135
	v_lshlrev_b32_e32 v5, 1, v138
	v_lshlrev_b32_e32 v6, 1, v139
	v_lshlrev_b32_e32 v7, 1, v140
	v_lshlrev_b32_e32 v8, 1, v141
	v_lshlrev_b32_e32 v9, 1, v142
	v_lshlrev_b32_e32 v10, 1, v143
	v_lshlrev_b32_e32 v11, 1, v144
	v_lshlrev_b32_e32 v12, 1, v145
	v_lshlrev_b32_e32 v13, 1, v146
	v_lshlrev_b32_e32 v14, 1, v147
	v_lshlrev_b32_e32 v15, 1, v148
	v_lshlrev_b32_e32 v16, 1, v149
	v_lshlrev_b32_e32 v17, 1, v150
	v_lshlrev_b32_e32 v18, 1, v151
	v_lshl_add_u32 v19, v0, 4, s6
	v_lshlrev_b32_e32 v134, 3, v0
	v_mul_u32_u24_e32 v0, 0x90, v154
	s_cselect_b32 s21, s2, 0xf448
	v_lshl_add_u32 v153, v133, 2, s6
	v_or_b32_e32 v155, 8, v154
	v_or_b32_e32 v156, 16, v154
	v_or_b32_e32 v157, 24, v154
	v_or_b32_e32 v158, 32, v154
	v_or_b32_e32 v159, 40, v154
	v_or_b32_e32 v160, 48, v154
	v_or_b32_e32 v161, 56, v154
	v_lshlrev_b32_e32 v5, 1, v134
	v_add_u32_e32 v3, v2, v3
	v_add_u32_e32 v4, v2, v4
	v_add_u32_e32 v162, v3, v5
	v_add_u32_e32 v163, v4, v5
	v_xor_b32_e32 v6, 16, v5
	v_add_u32_e32 v164, v3, v6
	v_add_u32_e32 v165, v4, v6
	v_xor_b32_e32 v6, 32, v5
	v_add_u32_e32 v166, v3, v6
	v_add_u32_e32 v167, v4, v6
	v_xor_b32_e32 v6, 48, v5
	v_add_u32_e32 v168, v3, v6
	v_add_u32_e32 v169, v4, v6
	v_xor_b32_e32 v6, 64, v5
	v_add_u32_e32 v180, v3, v6
	v_add_u32_e32 v181, v4, v6
	v_xor_b32_e32 v6, 0x50, v5
	v_add_u32_e32 v182, v3, v6
	v_add_u32_e32 v183, v4, v6
	v_xor_b32_e32 v6, 0x60, v5
	v_add_u32_e32 v184, v3, v6
	v_add_u32_e32 v185, v4, v6
	v_xor_b32_e32 v6, 0x70, v5
	v_add_u32_e32 v186, v3, v6
	v_add_u32_e32 v187, v4, v6
	v_add_u32_e32 v7, v19, v0
	v_sub_u32_e32 v7, v7, v5
	v_lshrrev_b32_e32 v8, 2, v154
	v_lshlrev_b32_e32 v8, 4, v8
	v_xor_b32_e32 v8, v8, v5
	v_add_u32_e32 v188, v7, v8
	v_xor_b32_e32 v9, 32, v8
	v_add_u32_e32 v244, v7, v9
	v_xor_b32_e32 v9, 64, v8
	v_add_u32_e32 v245, v7, v9
	v_xor_b32_e32 v9, 0x60, v8
	v_add_u32_e32 v246, v7, v9
	s_branch .LBB0_316

.LBB0_345:
	ds_write_b32 v152, v190 offset:9216
	s_waitcnt lgkmcnt(0)
	ds_read_b32 v137, v153 offset:9216
	s_cmpk_eq_i32 s26, 0x2b00
	s_cselect_b64 s[2:3], -1, 0
	s_cmpk_eq_i32 s25, 0x2b00
	s_cselect_b64 s[12:13], -1, 0
	s_waitcnt lgkmcnt(0)
	v_mul_f32_e32 v192, v46, v137
	v_mul_f32_e32 v193, v47, v137
	v_cvt_pk_bf16_f32 v192, v192, v193
	v_mul_f32_e32 v193, v48, v137
	v_mul_f32_e32 v137, v49, v137
	v_cvt_pk_bf16_f32 v137, v193, v137
	ds_write_b16 v162, v192
	ds_write_b16_d16_hi v162, v192 offset:144
	ds_write_b16 v162, v137 offset:288
	ds_write_b16_d16_hi v162, v137 offset:432
	ds_read_b32 v137, v153 offset:9232
	s_or_b64 s[2:3], s[12:13], s[2:3]
	s_and_b64 s[2:3], s[2:3], exec
	s_cselect_b32 s2, 0x20002, 0
	s_cselect_b32 s3, 0xfffcfffc, -1
	s_waitcnt lgkmcnt(0)
	v_mul_f32_e32 v192, v42, v137
	v_mul_f32_e32 v193, v43, v137
	v_cvt_pk_bf16_f32 v192, v192, v193
	v_mul_f32_e32 v193, v44, v137
	v_mul_f32_e32 v137, v45, v137
	v_cvt_pk_bf16_f32 v137, v193, v137
	ds_write_b16 v163, v192
	ds_write_b16_d16_hi v163, v192 offset:144
	ds_write_b16 v163, v137 offset:288
	ds_write_b16_d16_hi v163, v137 offset:432
	ds_read_b32 v137, v153 offset:9248
	s_waitcnt lgkmcnt(0)
	v_mul_f32_e32 v192, v62, v137
	v_mul_f32_e32 v193, v63, v137
	v_cvt_pk_bf16_f32 v192, v192, v193
	v_mul_f32_e32 v193, v64, v137
	v_mul_f32_e32 v137, v65, v137
	v_cvt_pk_bf16_f32 v137, v193, v137
	ds_write_b16 v164, v192
	ds_write_b16_d16_hi v164, v192 offset:144
	ds_write_b16 v164, v137 offset:288
	ds_write_b16_d16_hi v164, v137 offset:432
	ds_read_b32 v137, v153 offset:9264
	s_waitcnt lgkmcnt(0)
	v_mul_f32_e32 v192, v58, v137
	v_mul_f32_e32 v193, v59, v137
	v_cvt_pk_bf16_f32 v192, v192, v193
	v_mul_f32_e32 v193, v60, v137
	v_mul_f32_e32 v137, v61, v137
	v_cvt_pk_bf16_f32 v137, v193, v137
	ds_write_b16 v165, v192
	ds_write_b16_d16_hi v165, v192 offset:144
	ds_write_b16 v165, v137 offset:288
	ds_write_b16_d16_hi v165, v137 offset:432
	ds_read_b32 v137, v153 offset:9280
	s_waitcnt lgkmcnt(0)
	v_mul_f32_e32 v192, v70, v137
	v_mul_f32_e32 v193, v71, v137
	v_cvt_pk_bf16_f32 v192, v192, v193
	v_mul_f32_e32 v193, v72, v137
	v_mul_f32_e32 v137, v73, v137
	v_cvt_pk_bf16_f32 v137, v193, v137
	ds_write_b16 v166, v192
	ds_write_b16_d16_hi v166, v192 offset:144
	ds_write_b16 v166, v137 offset:288
	ds_write_b16_d16_hi v166, v137 offset:432
	ds_read_b32 v137, v153 offset:9296
	s_waitcnt lgkmcnt(0)
	v_mul_f32_e32 v192, v66, v137
	v_mul_f32_e32 v193, v67, v137
	v_cvt_pk_bf16_f32 v192, v192, v193
	v_mul_f32_e32 v193, v68, v137
	v_mul_f32_e32 v137, v69, v137
	v_cvt_pk_bf16_f32 v137, v193, v137
	ds_write_b16 v167, v192
	ds_write_b16_d16_hi v167, v192 offset:144
	ds_write_b16 v167, v137 offset:288
	ds_write_b16_d16_hi v167, v137 offset:432
	ds_read_b32 v137, v153 offset:9312
	s_waitcnt lgkmcnt(0)
	v_mul_f32_e32 v192, v82, v137
	v_mul_f32_e32 v193, v83, v137
	v_cvt_pk_bf16_f32 v192, v192, v193
	v_mul_f32_e32 v193, v84, v137
	v_mul_f32_e32 v137, v85, v137
	v_cvt_pk_bf16_f32 v137, v193, v137
	ds_write_b16 v168, v192
	ds_write_b16_d16_hi v168, v192 offset:144
	ds_write_b16 v168, v137 offset:288
	ds_write_b16_d16_hi v168, v137 offset:432
	ds_read_b32 v137, v153 offset:9328
	s_waitcnt lgkmcnt(0)
	v_mul_f32_e32 v192, v78, v137
	v_mul_f32_e32 v193, v79, v137
	v_cvt_pk_bf16_f32 v192, v192, v193
	v_mul_f32_e32 v193, v80, v137
	v_mul_f32_e32 v137, v81, v137
	v_cvt_pk_bf16_f32 v137, v193, v137
	ds_write_b16 v169, v192
	ds_write_b16_d16_hi v169, v192 offset:144
	ds_write_b16 v169, v137 offset:288
	ds_write_b16_d16_hi v169, v137 offset:432
	ds_read_b32 v137, v153 offset:9344
	s_waitcnt lgkmcnt(0)
	v_mul_f32_e32 v192, v94, v137
	v_mul_f32_e32 v193, v95, v137
	v_cvt_pk_bf16_f32 v192, v192, v193
	v_mul_f32_e32 v193, v96, v137
	v_mul_f32_e32 v137, v97, v137
	v_cvt_pk_bf16_f32 v137, v193, v137
	ds_write_b16 v180, v192
	ds_write_b16_d16_hi v180, v192 offset:144
	ds_write_b16 v180, v137 offset:288
	ds_write_b16_d16_hi v180, v137 offset:432
	ds_read_b32 v137, v153 offset:9360
	s_waitcnt lgkmcnt(0)
	v_mul_f32_e32 v192, v90, v137
	v_mul_f32_e32 v193, v91, v137
	v_cvt_pk_bf16_f32 v192, v192, v193
	v_mul_f32_e32 v193, v92, v137
	v_mul_f32_e32 v137, v93, v137
	v_cvt_pk_bf16_f32 v137, v193, v137
	ds_write_b16 v181, v192
	ds_write_b16_d16_hi v181, v192 offset:144
	ds_write_b16 v181, v137 offset:288
	ds_write_b16_d16_hi v181, v137 offset:432
	ds_read_b32 v137, v153 offset:9376
	s_waitcnt lgkmcnt(0)
	v_mul_f32_e32 v192, v102, v137
	v_mul_f32_e32 v193, v103, v137
	v_cvt_pk_bf16_f32 v192, v192, v193
	v_mul_f32_e32 v193, v104, v137
	v_mul_f32_e32 v137, v105, v137
	v_cvt_pk_bf16_f32 v137, v193, v137
	ds_write_b16 v182, v192
	ds_write_b16_d16_hi v182, v192 offset:144
	ds_write_b16 v182, v137 offset:288
	ds_write_b16_d16_hi v182, v137 offset:432
	ds_read_b32 v137, v153 offset:9392
	s_waitcnt lgkmcnt(0)
	v_mul_f32_e32 v192, v98, v137
	v_mul_f32_e32 v193, v99, v137
	v_cvt_pk_bf16_f32 v192, v192, v193
	v_mul_f32_e32 v193, v100, v137
	v_mul_f32_e32 v137, v101, v137
	v_cvt_pk_bf16_f32 v137, v193, v137
	ds_write_b16 v183, v192
	ds_write_b16_d16_hi v183, v192 offset:144
	ds_write_b16 v183, v137 offset:288
	ds_write_b16_d16_hi v183, v137 offset:432
	ds_read_b32 v137, v153 offset:9408
	s_waitcnt lgkmcnt(0)
	v_mul_f32_e32 v192, v118, v137
	v_mul_f32_e32 v193, v119, v137
	v_cvt_pk_bf16_f32 v192, v192, v193
	v_mul_f32_e32 v193, v120, v137
	v_mul_f32_e32 v137, v121, v137
	v_cvt_pk_bf16_f32 v137, v193, v137
	ds_write_b16 v184, v192
	ds_write_b16_d16_hi v184, v192 offset:144
	ds_write_b16 v184, v137 offset:288
	ds_write_b16_d16_hi v184, v137 offset:432
	ds_read_b32 v137, v153 offset:9424
	s_waitcnt lgkmcnt(0)
	v_mul_f32_e32 v192, v114, v137
	v_mul_f32_e32 v193, v115, v137
	v_cvt_pk_bf16_f32 v192, v192, v193
	v_mul_f32_e32 v193, v116, v137
	v_mul_f32_e32 v137, v117, v137
	v_cvt_pk_bf16_f32 v137, v193, v137
	ds_write_b16 v185, v192
	ds_write_b16_d16_hi v185, v192 offset:144
	ds_write_b16 v185, v137 offset:288
	ds_write_b16_d16_hi v185, v137 offset:432
	ds_read_b32 v137, v153 offset:9440
	s_waitcnt lgkmcnt(0)
	v_mul_f32_e32 v192, v126, v137
	v_mul_f32_e32 v193, v127, v137
	v_cvt_pk_bf16_f32 v192, v192, v193
	v_mul_f32_e32 v193, v128, v137
	v_mul_f32_e32 v137, v129, v137
	v_cvt_pk_bf16_f32 v137, v193, v137
	ds_write_b16 v186, v192
	ds_write_b16_d16_hi v186, v192 offset:144
	ds_write_b16 v186, v137 offset:288
	ds_write_b16_d16_hi v186, v137 offset:432
	ds_read_b32 v137, v153 offset:9456
	s_waitcnt lgkmcnt(0)
	v_mul_f32_e32 v192, v122, v137
	v_mul_f32_e32 v193, v123, v137
	v_cvt_pk_bf16_f32 v192, v192, v193
	v_mul_f32_e32 v193, v124, v137
	v_mul_f32_e32 v137, v125, v137
	v_cvt_pk_bf16_f32 v137, v193, v137
	ds_write_b16 v187, v192
	ds_write_b16_d16_hi v187, v192 offset:144
	ds_write_b16 v187, v137 offset:288
	ds_write_b16_d16_hi v187, v137 offset:432
	s_waitcnt lgkmcnt(0)
	ds_read_b128 v[192:195], v188
	s_waitcnt lgkmcnt(0)
	v_add_u32_e32 v137, s2, v192
	v_and_b32_e32 v192, s3, v137
	v_add_u32_e32 v137, s2, v193
	v_and_b32_e32 v193, s3, v137
	v_add_u32_e32 v137, s2, v194
	v_and_b32_e32 v194, s3, v137
	v_add_u32_e32 v137, s2, v195
	v_and_b32_e32 v195, s3, v137
	v_add_u32_e32 v137, s28, v154
	v_mad_u64_u32 v[196:197], s[12:13], v137, s25, 0
	v_ashrrev_i32_e32 v199, 31, v137
	v_mov_b32_e32 v198, v197
	v_mad_u64_u32 v[198:199], s[12:13], v199, s25, v[198:199]
	v_mov_b32_e32 v197, v198
	v_lshl_add_u64 v[196:197], v[196:197], 1, s[8:9]
	v_lshl_add_u64 v[196:197], v[196:197], 0, v[0:1]
	global_store_dwordx4 v[196:197], v[192:195], off
	ds_read_b128 v[192:195], v244 offset:1152
	s_waitcnt lgkmcnt(0)
	v_add_u32_e32 v137, s2, v192
	v_and_b32_e32 v192, s3, v137
	v_add_u32_e32 v137, s2, v193
	v_and_b32_e32 v193, s3, v137
	v_add_u32_e32 v137, s2, v194
	v_and_b32_e32 v194, s3, v137
	v_add_u32_e32 v137, s2, v195
	v_and_b32_e32 v195, s3, v137
	v_add_u32_e32 v137, s28, v155
	v_mad_u64_u32 v[196:197], s[12:13], v137, s25, 0
	v_ashrrev_i32_e32 v199, 31, v137
	v_mov_b32_e32 v198, v197
	v_mad_u64_u32 v[198:199], s[12:13], v199, s25, v[198:199]
	v_mov_b32_e32 v197, v198
	v_lshl_add_u64 v[196:197], v[196:197], 1, s[8:9]
	v_lshl_add_u64 v[196:197], v[196:197], 0, v[0:1]
	global_store_dwordx4 v[196:197], v[192:195], off
	ds_read_b128 v[192:195], v245 offset:2304
	s_waitcnt lgkmcnt(0)
	v_add_u32_e32 v137, s2, v192
	v_and_b32_e32 v192, s3, v137
	v_add_u32_e32 v137, s2, v193
	v_and_b32_e32 v193, s3, v137
	v_add_u32_e32 v137, s2, v194
	v_and_b32_e32 v194, s3, v137
	v_add_u32_e32 v137, s2, v195
	v_and_b32_e32 v195, s3, v137
	v_add_u32_e32 v137, s28, v156
	v_mad_u64_u32 v[196:197], s[12:13], v137, s25, 0
	v_ashrrev_i32_e32 v199, 31, v137
	v_mov_b32_e32 v198, v197
	v_mad_u64_u32 v[198:199], s[12:13], v199, s25, v[198:199]
	v_mov_b32_e32 v197, v198
	v_lshl_add_u64 v[196:197], v[196:197], 1, s[8:9]
	v_lshl_add_u64 v[196:197], v[196:197], 0, v[0:1]
	global_store_dwordx4 v[196:197], v[192:195], off
	ds_read_b128 v[192:195], v246 offset:3456
	s_waitcnt lgkmcnt(0)
	v_add_u32_e32 v137, s2, v192
	v_and_b32_e32 v192, s3, v137
	v_add_u32_e32 v137, s2, v193
	v_and_b32_e32 v193, s3, v137
	v_add_u32_e32 v137, s2, v194
	v_and_b32_e32 v194, s3, v137
	v_add_u32_e32 v137, s2, v195
	v_and_b32_e32 v195, s3, v137
	v_add_u32_e32 v137, s28, v157
	v_mad_u64_u32 v[196:197], s[12:13], v137, s25, 0
	v_ashrrev_i32_e32 v199, 31, v137
	v_mov_b32_e32 v198, v197
	v_mad_u64_u32 v[198:199], s[12:13], v199, s25, v[198:199]
	v_mov_b32_e32 v197, v198
	v_lshl_add_u64 v[196:197], v[196:197], 1, s[8:9]
	v_lshl_add_u64 v[196:197], v[196:197], 0, v[0:1]
	global_store_dwordx4 v[196:197], v[192:195], off
	ds_read_b128 v[192:195], v188 offset:4608
	s_waitcnt lgkmcnt(0)
	v_add_u32_e32 v137, s2, v192
	v_and_b32_e32 v192, s3, v137
	v_add_u32_e32 v137, s2, v193
	v_and_b32_e32 v193, s3, v137
	v_add_u32_e32 v137, s2, v194
	v_and_b32_e32 v194, s3, v137
	v_add_u32_e32 v137, s2, v195
	v_and_b32_e32 v195, s3, v137
	v_add_u32_e32 v137, s28, v158
	v_mad_u64_u32 v[196:197], s[12:13], v137, s25, 0
	v_ashrrev_i32_e32 v199, 31, v137
	v_mov_b32_e32 v198, v197
	v_mad_u64_u32 v[198:199], s[12:13], v199, s25, v[198:199]
	v_mov_b32_e32 v197, v198
	v_lshl_add_u64 v[196:197], v[196:197], 1, s[8:9]
	v_lshl_add_u64 v[196:197], v[196:197], 0, v[0:1]
	global_store_dwordx4 v[196:197], v[192:195], off
	ds_read_b128 v[192:195], v244 offset:5760
	s_waitcnt lgkmcnt(0)
	v_add_u32_e32 v137, s2, v192
	v_and_b32_e32 v192, s3, v137
	v_add_u32_e32 v137, s2, v193
	v_and_b32_e32 v193, s3, v137
	v_add_u32_e32 v137, s2, v194
	v_and_b32_e32 v194, s3, v137
	v_add_u32_e32 v137, s2, v195
	v_and_b32_e32 v195, s3, v137
	v_add_u32_e32 v137, s28, v159
	v_mad_u64_u32 v[196:197], s[12:13], v137, s25, 0
	v_ashrrev_i32_e32 v199, 31, v137
	v_mov_b32_e32 v198, v197
	v_mad_u64_u32 v[198:199], s[12:13], v199, s25, v[198:199]
	v_mov_b32_e32 v197, v198
	v_lshl_add_u64 v[196:197], v[196:197], 1, s[8:9]
	v_lshl_add_u64 v[196:197], v[196:197], 0, v[0:1]
	global_store_dwordx4 v[196:197], v[192:195], off
	ds_read_b128 v[192:195], v245 offset:6912
	s_waitcnt lgkmcnt(0)
	v_add_u32_e32 v137, s2, v192
	v_and_b32_e32 v192, s3, v137
	v_add_u32_e32 v137, s2, v193
	v_and_b32_e32 v193, s3, v137
	v_add_u32_e32 v137, s2, v194
	v_and_b32_e32 v194, s3, v137
	v_add_u32_e32 v137, s2, v195
	v_and_b32_e32 v195, s3, v137
	v_add_u32_e32 v137, s28, v160
	v_mad_u64_u32 v[196:197], s[12:13], v137, s25, 0
	v_ashrrev_i32_e32 v199, 31, v137
	v_mov_b32_e32 v198, v197
	v_mad_u64_u32 v[198:199], s[12:13], v199, s25, v[198:199]
	v_mov_b32_e32 v197, v198
	v_lshl_add_u64 v[196:197], v[196:197], 1, s[8:9]
	v_lshl_add_u64 v[196:197], v[196:197], 0, v[0:1]
	global_store_dwordx4 v[196:197], v[192:195], off
	ds_read_b128 v[192:195], v246 offset:8064
	s_waitcnt lgkmcnt(0)
	v_add_u32_e32 v137, s2, v192
	v_and_b32_e32 v192, s3, v137
	v_add_u32_e32 v137, s2, v193
	v_and_b32_e32 v193, s3, v137
	v_add_u32_e32 v137, s2, v194
	v_and_b32_e32 v194, s3, v137
	v_add_u32_e32 v137, s2, v195
	v_and_b32_e32 v195, s3, v137
	v_add_u32_e32 v137, s28, v161
	v_mad_u64_u32 v[196:197], s[2:3], v137, s25, 0
	v_ashrrev_i32_e32 v199, 31, v137
	v_mov_b32_e32 v198, v197
	v_mad_u64_u32 v[198:199], s[2:3], v199, s25, v[198:199]
	v_mov_b32_e32 v197, v198
	v_lshl_add_u64 v[196:197], v[196:197], 1, s[8:9]
	v_lshl_add_u64 v[196:197], v[196:197], 0, v[0:1]
	global_store_dwordx4 v[196:197], v[192:195], off
	s_waitcnt lgkmcnt(0)

.LBB0_367:
	s_waitcnt vmcnt(16)
	ds_write_b32 v152, v191 offset:9216
	s_waitcnt lgkmcnt(0)
	ds_read_b32 v0, v153 offset:9216
	s_cmpk_eq_i32 s24, 0x2b00
	s_cselect_b64 s[2:3], -1, 0
	s_cmpk_eq_i32 s23, 0x2b00
	s_cselect_b64 s[10:11], -1, 0
	s_waitcnt vmcnt(15) lgkmcnt(0)
	v_mul_f32_e32 v137, v2, v0
	v_mul_f32_e32 v192, v3, v0
	v_cvt_pk_bf16_f32 v137, v137, v192
	v_mul_f32_e32 v192, v4, v0
	v_mul_f32_e32 v0, v5, v0
	v_cvt_pk_bf16_f32 v0, v192, v0
	ds_write_b16 v162, v137
	ds_write_b16_d16_hi v162, v137 offset:144
	ds_write_b16 v162, v0 offset:288
	ds_write_b16_d16_hi v162, v0 offset:432
	ds_read_b32 v0, v153 offset:9232
	s_or_b64 s[2:3], s[10:11], s[2:3]
	s_and_b64 s[2:3], s[2:3], exec
	s_cselect_b32 s2, 0x20002, 0
	s_cselect_b32 s3, 0xfffcfffc, -1
	s_waitcnt vmcnt(14) lgkmcnt(0)
	v_mul_f32_e32 v137, v6, v0
	v_mul_f32_e32 v192, v7, v0
	v_cvt_pk_bf16_f32 v137, v137, v192
	v_mul_f32_e32 v192, v8, v0
	v_mul_f32_e32 v0, v9, v0
	v_cvt_pk_bf16_f32 v0, v192, v0
	ds_write_b16 v163, v137
	ds_write_b16_d16_hi v163, v137 offset:144
	ds_write_b16 v163, v0 offset:288
	ds_write_b16_d16_hi v163, v0 offset:432
	ds_read_b32 v0, v153 offset:9248
	s_andn2_b64 vcc, exec, s[12:13]
	s_waitcnt vmcnt(13) lgkmcnt(0)
	v_mul_f32_e32 v137, v10, v0
	v_mul_f32_e32 v192, v11, v0
	v_cvt_pk_bf16_f32 v137, v137, v192
	v_mul_f32_e32 v192, v12, v0
	v_mul_f32_e32 v0, v13, v0
	v_cvt_pk_bf16_f32 v0, v192, v0
	ds_write_b16 v164, v137
	ds_write_b16_d16_hi v164, v137 offset:144
	ds_write_b16 v164, v0 offset:288
	ds_write_b16_d16_hi v164, v0 offset:432
	ds_read_b32 v0, v153 offset:9264
	s_waitcnt vmcnt(12) lgkmcnt(0)
	v_mul_f32_e32 v137, v14, v0
	v_mul_f32_e32 v192, v15, v0
	v_cvt_pk_bf16_f32 v137, v137, v192
	v_mul_f32_e32 v192, v16, v0
	v_mul_f32_e32 v0, v17, v0
	v_cvt_pk_bf16_f32 v0, v192, v0
	ds_write_b16 v165, v137
	ds_write_b16_d16_hi v165, v137 offset:144
	ds_write_b16 v165, v0 offset:288
	ds_write_b16_d16_hi v165, v0 offset:432
	ds_read_b32 v0, v153 offset:9280
	s_waitcnt vmcnt(11) lgkmcnt(0)
	v_mul_f32_e32 v137, v18, v0
	v_mul_f32_e32 v192, v19, v0
	v_cvt_pk_bf16_f32 v137, v137, v192
	v_mul_f32_e32 v192, v20, v0
	v_mul_f32_e32 v0, v21, v0
	v_cvt_pk_bf16_f32 v0, v192, v0
	ds_write_b16 v166, v137
	ds_write_b16_d16_hi v166, v137 offset:144
	ds_write_b16 v166, v0 offset:288
	ds_write_b16_d16_hi v166, v0 offset:432
	ds_read_b32 v0, v153 offset:9296
	s_waitcnt vmcnt(10) lgkmcnt(0)
	v_mul_f32_e32 v137, v22, v0
	v_mul_f32_e32 v192, v23, v0
	v_cvt_pk_bf16_f32 v137, v137, v192
	v_mul_f32_e32 v192, v24, v0
	v_mul_f32_e32 v0, v25, v0
	v_cvt_pk_bf16_f32 v0, v192, v0
	ds_write_b16 v167, v137
	ds_write_b16_d16_hi v167, v137 offset:144
	ds_write_b16 v167, v0 offset:288
	ds_write_b16_d16_hi v167, v0 offset:432
	ds_read_b32 v0, v153 offset:9312
	s_waitcnt vmcnt(9) lgkmcnt(0)
	v_mul_f32_e32 v137, v26, v0
	v_mul_f32_e32 v192, v27, v0
	v_cvt_pk_bf16_f32 v137, v137, v192
	v_mul_f32_e32 v192, v28, v0
	v_mul_f32_e32 v0, v29, v0
	v_cvt_pk_bf16_f32 v0, v192, v0
	ds_write_b16 v168, v137
	ds_write_b16_d16_hi v168, v137 offset:144
	ds_write_b16 v168, v0 offset:288
	ds_write_b16_d16_hi v168, v0 offset:432
	ds_read_b32 v0, v153 offset:9328
	s_waitcnt vmcnt(8) lgkmcnt(0)
	v_mul_f32_e32 v137, v30, v0
	v_mul_f32_e32 v192, v31, v0
	v_cvt_pk_bf16_f32 v137, v137, v192
	v_mul_f32_e32 v192, v32, v0
	v_mul_f32_e32 v0, v33, v0
	v_cvt_pk_bf16_f32 v0, v192, v0
	ds_write_b16 v169, v137
	ds_write_b16_d16_hi v169, v137 offset:144
	ds_write_b16 v169, v0 offset:288
	ds_write_b16_d16_hi v169, v0 offset:432
	ds_read_b32 v0, v153 offset:9344
	s_waitcnt vmcnt(7) lgkmcnt(0)
	v_mul_f32_e32 v137, v34, v0
	v_mul_f32_e32 v192, v35, v0
	v_cvt_pk_bf16_f32 v137, v137, v192
	v_mul_f32_e32 v192, v36, v0
	v_mul_f32_e32 v0, v37, v0
	v_cvt_pk_bf16_f32 v0, v192, v0
	ds_write_b16 v180, v137
	ds_write_b16_d16_hi v180, v137 offset:144
	ds_write_b16 v180, v0 offset:288
	ds_write_b16_d16_hi v180, v0 offset:432
	ds_read_b32 v0, v153 offset:9360
	s_waitcnt vmcnt(6) lgkmcnt(0)
	v_mul_f32_e32 v137, v38, v0
	v_mul_f32_e32 v192, v39, v0
	v_cvt_pk_bf16_f32 v137, v137, v192
	v_mul_f32_e32 v192, v40, v0
	v_mul_f32_e32 v0, v41, v0
	v_cvt_pk_bf16_f32 v0, v192, v0
	ds_write_b16 v181, v137
	ds_write_b16_d16_hi v181, v137 offset:144
	ds_write_b16 v181, v0 offset:288
	ds_write_b16_d16_hi v181, v0 offset:432
	ds_read_b32 v0, v153 offset:9376
	s_waitcnt vmcnt(5) lgkmcnt(0)
	v_mul_f32_e32 v137, v50, v0
	v_mul_f32_e32 v192, v51, v0
	v_cvt_pk_bf16_f32 v137, v137, v192
	v_mul_f32_e32 v192, v52, v0
	v_mul_f32_e32 v0, v53, v0
	v_cvt_pk_bf16_f32 v0, v192, v0
	ds_write_b16 v182, v137
	ds_write_b16_d16_hi v182, v137 offset:144
	ds_write_b16 v182, v0 offset:288
	ds_write_b16_d16_hi v182, v0 offset:432
	ds_read_b32 v0, v153 offset:9392
	s_waitcnt vmcnt(4) lgkmcnt(0)
	v_mul_f32_e32 v137, v54, v0
	v_mul_f32_e32 v192, v55, v0
	v_cvt_pk_bf16_f32 v137, v137, v192
	v_mul_f32_e32 v192, v56, v0
	v_mul_f32_e32 v0, v57, v0
	v_cvt_pk_bf16_f32 v0, v192, v0
	ds_write_b16 v183, v137
	ds_write_b16_d16_hi v183, v137 offset:144
	ds_write_b16 v183, v0 offset:288
	ds_write_b16_d16_hi v183, v0 offset:432
	ds_read_b32 v0, v153 offset:9408
	s_waitcnt vmcnt(3) lgkmcnt(0)
	v_mul_f32_e32 v137, v74, v0
	v_mul_f32_e32 v192, v75, v0
	v_cvt_pk_bf16_f32 v137, v137, v192
	v_mul_f32_e32 v192, v76, v0
	v_mul_f32_e32 v0, v77, v0
	v_cvt_pk_bf16_f32 v0, v192, v0
	ds_write_b16 v184, v137
	ds_write_b16_d16_hi v184, v137 offset:144
	ds_write_b16 v184, v0 offset:288
	ds_write_b16_d16_hi v184, v0 offset:432
	ds_read_b32 v0, v153 offset:9424
	s_waitcnt vmcnt(2) lgkmcnt(0)
	v_mul_f32_e32 v137, v86, v0
	v_mul_f32_e32 v192, v87, v0
	v_cvt_pk_bf16_f32 v137, v137, v192
	v_mul_f32_e32 v192, v88, v0
	v_mul_f32_e32 v0, v89, v0
	v_cvt_pk_bf16_f32 v0, v192, v0
	ds_write_b16 v185, v137
	ds_write_b16_d16_hi v185, v137 offset:144
	ds_write_b16 v185, v0 offset:288
	ds_write_b16_d16_hi v185, v0 offset:432
	ds_read_b32 v0, v153 offset:9440
	s_waitcnt vmcnt(1) lgkmcnt(0)
	v_mul_f32_e32 v137, v106, v0
	v_mul_f32_e32 v192, v107, v0
	v_cvt_pk_bf16_f32 v137, v137, v192
	v_mul_f32_e32 v192, v108, v0
	v_mul_f32_e32 v0, v109, v0
	v_cvt_pk_bf16_f32 v0, v192, v0
	ds_write_b16 v186, v137
	ds_write_b16_d16_hi v186, v137 offset:144
	ds_write_b16 v186, v0 offset:288
	ds_write_b16_d16_hi v186, v0 offset:432
	ds_read_b32 v0, v153 offset:9456
	s_waitcnt vmcnt(0) lgkmcnt(0)
	v_mul_f32_e32 v137, v110, v0
	v_mul_f32_e32 v192, v111, v0
	v_cvt_pk_bf16_f32 v137, v137, v192
	v_mul_f32_e32 v192, v112, v0
	v_mul_f32_e32 v0, v113, v0
	v_cvt_pk_bf16_f32 v0, v192, v0
	ds_write_b16 v187, v137
	ds_write_b16_d16_hi v187, v137 offset:144
	ds_write_b16 v187, v0 offset:288
	ds_write_b16_d16_hi v187, v0 offset:432
	s_waitcnt lgkmcnt(0)
	ds_read_b128 v[192:195], v188
	s_waitcnt lgkmcnt(0)
	v_add_u32_e32 v0, s2, v192
	v_and_b32_e32 v192, s3, v0
	v_add_u32_e32 v0, s2, v193
	v_and_b32_e32 v193, s3, v0
	v_add_u32_e32 v0, s2, v194
	v_and_b32_e32 v194, s3, v0
	v_add_u32_e32 v0, s2, v195
	v_and_b32_e32 v195, s3, v0
	v_add_u32_e32 v0, s27, v154
	v_mad_u64_u32 v[196:197], s[10:11], v0, s23, 0
	v_ashrrev_i32_e32 v137, 31, v0
	v_mov_b32_e32 v0, v197
	v_mad_u64_u32 v[198:199], s[10:11], v137, s23, v[0:1]
	v_mov_b32_e32 v197, v198
	v_lshl_add_u64 v[196:197], v[196:197], 1, s[6:7]
	v_lshlrev_b32_e32 v0, 1, v134
	v_lshl_add_u64 v[196:197], v[196:197], 0, v[0:1]
	global_store_dwordx4 v[196:197], v[192:195], off
	ds_read_b128 v[192:195], v244 offset:1152
	s_waitcnt lgkmcnt(0)
	v_add_u32_e32 v137, s2, v192
	v_and_b32_e32 v192, s3, v137
	v_add_u32_e32 v137, s2, v193
	v_and_b32_e32 v193, s3, v137
	v_add_u32_e32 v137, s2, v194
	v_and_b32_e32 v194, s3, v137
	v_add_u32_e32 v137, s2, v195
	v_and_b32_e32 v195, s3, v137
	v_add_u32_e32 v137, s27, v155
	v_mad_u64_u32 v[196:197], s[10:11], v137, s23, 0
	v_ashrrev_i32_e32 v199, 31, v137
	v_mov_b32_e32 v198, v197
	v_mad_u64_u32 v[198:199], s[10:11], v199, s23, v[198:199]
	v_mov_b32_e32 v197, v198
	v_lshl_add_u64 v[196:197], v[196:197], 1, s[6:7]
	v_lshl_add_u64 v[196:197], v[196:197], 0, v[0:1]
	global_store_dwordx4 v[196:197], v[192:195], off
	ds_read_b128 v[192:195], v245 offset:2304
	s_waitcnt lgkmcnt(0)
	v_add_u32_e32 v137, s2, v192
	v_and_b32_e32 v192, s3, v137
	v_add_u32_e32 v137, s2, v193
	v_and_b32_e32 v193, s3, v137
	v_add_u32_e32 v137, s2, v194
	v_and_b32_e32 v194, s3, v137
	v_add_u32_e32 v137, s2, v195
	v_and_b32_e32 v195, s3, v137
	v_add_u32_e32 v137, s27, v156
	v_mad_u64_u32 v[196:197], s[10:11], v137, s23, 0
	v_ashrrev_i32_e32 v199, 31, v137
	v_mov_b32_e32 v198, v197
	v_mad_u64_u32 v[198:199], s[10:11], v199, s23, v[198:199]
	v_mov_b32_e32 v197, v198
	v_lshl_add_u64 v[196:197], v[196:197], 1, s[6:7]
	v_lshl_add_u64 v[196:197], v[196:197], 0, v[0:1]
	global_store_dwordx4 v[196:197], v[192:195], off
	ds_read_b128 v[192:195], v246 offset:3456
	s_waitcnt lgkmcnt(0)
	v_add_u32_e32 v137, s2, v192
	v_and_b32_e32 v192, s3, v137
	v_add_u32_e32 v137, s2, v193
	v_and_b32_e32 v193, s3, v137
	v_add_u32_e32 v137, s2, v194
	v_and_b32_e32 v194, s3, v137
	v_add_u32_e32 v137, s2, v195
	v_and_b32_e32 v195, s3, v137
	v_add_u32_e32 v137, s27, v157
	v_mad_u64_u32 v[196:197], s[10:11], v137, s23, 0
	v_ashrrev_i32_e32 v199, 31, v137
	v_mov_b32_e32 v198, v197
	v_mad_u64_u32 v[198:199], s[10:11], v199, s23, v[198:199]
	v_mov_b32_e32 v197, v198
	v_lshl_add_u64 v[196:197], v[196:197], 1, s[6:7]
	v_lshl_add_u64 v[196:197], v[196:197], 0, v[0:1]
	global_store_dwordx4 v[196:197], v[192:195], off
	ds_read_b128 v[192:195], v188 offset:4608
	s_waitcnt lgkmcnt(0)
	v_add_u32_e32 v137, s2, v192
	v_and_b32_e32 v192, s3, v137
	v_add_u32_e32 v137, s2, v193
	v_and_b32_e32 v193, s3, v137
	v_add_u32_e32 v137, s2, v194
	v_and_b32_e32 v194, s3, v137
	v_add_u32_e32 v137, s2, v195
	v_and_b32_e32 v195, s3, v137
	v_add_u32_e32 v137, s27, v158
	v_mad_u64_u32 v[196:197], s[10:11], v137, s23, 0
	v_ashrrev_i32_e32 v199, 31, v137
	v_mov_b32_e32 v198, v197
	v_mad_u64_u32 v[198:199], s[10:11], v199, s23, v[198:199]
	v_mov_b32_e32 v197, v198
	v_lshl_add_u64 v[196:197], v[196:197], 1, s[6:7]
	v_lshl_add_u64 v[196:197], v[196:197], 0, v[0:1]
	global_store_dwordx4 v[196:197], v[192:195], off
	ds_read_b128 v[192:195], v244 offset:5760
	s_waitcnt lgkmcnt(0)
	v_add_u32_e32 v137, s2, v192
	v_and_b32_e32 v192, s3, v137
	v_add_u32_e32 v137, s2, v193
	v_and_b32_e32 v193, s3, v137
	v_add_u32_e32 v137, s2, v194
	v_and_b32_e32 v194, s3, v137
	v_add_u32_e32 v137, s2, v195
	v_and_b32_e32 v195, s3, v137
	v_add_u32_e32 v137, s27, v159
	v_mad_u64_u32 v[196:197], s[10:11], v137, s23, 0
	v_ashrrev_i32_e32 v199, 31, v137
	v_mov_b32_e32 v198, v197
	v_mad_u64_u32 v[198:199], s[10:11], v199, s23, v[198:199]
	v_mov_b32_e32 v197, v198
	v_lshl_add_u64 v[196:197], v[196:197], 1, s[6:7]
	v_lshl_add_u64 v[196:197], v[196:197], 0, v[0:1]
	global_store_dwordx4 v[196:197], v[192:195], off
	ds_read_b128 v[192:195], v245 offset:6912
	s_waitcnt lgkmcnt(0)
	v_add_u32_e32 v137, s2, v192
	v_and_b32_e32 v192, s3, v137
	v_add_u32_e32 v137, s2, v193
	v_and_b32_e32 v193, s3, v137
	v_add_u32_e32 v137, s2, v194
	v_and_b32_e32 v194, s3, v137
	v_add_u32_e32 v137, s2, v195
	v_and_b32_e32 v195, s3, v137
	v_add_u32_e32 v137, s27, v160
	v_mad_u64_u32 v[196:197], s[10:11], v137, s23, 0
	v_ashrrev_i32_e32 v199, 31, v137
	v_mov_b32_e32 v198, v197
	v_mad_u64_u32 v[198:199], s[10:11], v199, s23, v[198:199]
	v_mov_b32_e32 v197, v198
	v_lshl_add_u64 v[196:197], v[196:197], 1, s[6:7]
	v_lshl_add_u64 v[196:197], v[196:197], 0, v[0:1]
	global_store_dwordx4 v[196:197], v[192:195], off
	ds_read_b128 v[192:195], v246 offset:8064
	s_mov_b64 s[10:11], -1
	s_waitcnt lgkmcnt(0)
	v_add_u32_e32 v137, s2, v192
	v_and_b32_e32 v192, s3, v137
	v_add_u32_e32 v137, s2, v193
	v_and_b32_e32 v193, s3, v137
	v_add_u32_e32 v137, s2, v194
	v_and_b32_e32 v194, s3, v137
	v_add_u32_e32 v137, s2, v195
	v_and_b32_e32 v195, s3, v137
	v_add_u32_e32 v137, s27, v161
	v_mad_u64_u32 v[196:197], s[2:3], v137, s23, 0
	v_ashrrev_i32_e32 v199, 31, v137
	v_mov_b32_e32 v198, v197
	v_mad_u64_u32 v[198:199], s[2:3], v199, s23, v[198:199]
	v_mov_b32_e32 v197, v198
	v_lshl_add_u64 v[196:197], v[196:197], 1, s[6:7]
	v_lshl_add_u64 v[196:197], v[196:197], 0, v[0:1]
	global_store_dwordx4 v[196:197], v[192:195], off
	s_waitcnt lgkmcnt(0)
	s_cbranch_vccnz .LBB0_346
	s_add_i32 s31, s30, 16
	s_cmp_ge_i32 s31, s22
	s_cselect_b64 s[10:11], -1, 0
	s_and_b64 vcc, exec, s[10:11]
	s_cbranch_vccnz .LBB0_345
	s_cmp_gt_i32 s30, 0xaaef
	s_cselect_b64 s[16:17], -1, 0
	s_and_b64 s[2:3], s[16:17], exec
	s_cselect_b32 s29, 0xffff5500, 0
	s_cselect_b32 s2, 0x15600000, 0
	s_add_i32 s29, s29, s31
	s_add_u32 s6, s56, s2
	s_addc_u32 s7, s57, 0
	s_cmpk_gt_i32 s29, 0x19ff
	s_mov_b64 s[64:65], -1
	s_cbranch_scc0 .LBB0_382
	s_cmpk_gt_u32 s29, 0x29ff
	s_cbranch_scc0 .LBB0_379
	s_and_b64 s[2:3], s[16:17], exec
	s_cselect_b32 s33, 0x2b00000, 0
	s_cmpk_gt_u32 s29, 0x54ff
	s_cbranch_scc0 .LBB0_376
	s_mov_b64 s[18:19], -1
	s_cmpk_gt_u32 s29, 0x7fff
	s_mov_b64 s[34:35], -1
	s_cbranch_scc0 .LBB0_374
	v_readlane_b32 s36, v252, 4
	s_add_i32 s27, s29, 0xffff8000
	s_lshl_b32 s2, s33, 2
	v_readlane_b32 s38, v252, 6
	v_readlane_b32 s39, v252, 7
	s_add_u32 s2, s38, s2
	s_addc_u32 s3, s39, 0
	s_add_u32 s12, s6, 0x10000000
	v_readlane_b32 s37, v252, 5
	v_readlane_b32 s40, v252, 8
	v_readlane_b32 s41, v252, 9
	v_readlane_b32 s42, v252, 10
	v_readlane_b32 s43, v252, 11
	s_addc_u32 s13, s7, 0
	s_mov_b64 s[34:35], 0

.LBB0_859:
	s_or_b64 exec, exec, s[0:1]
	s_add_u32 s20, s58, 0x5400000
	v_readlane_b32 s0, v254, 13
	v_readlane_b32 s24, v252, 4
	s_addc_u32 s21, s0, 0
	s_mul_i32 s0, s78, 0x20400
	v_readlane_b32 s28, v252, 8
	v_readlane_b32 s29, v252, 9
	s_add_u32 s10, s28, s0
	v_readlane_b32 s30, v252, 10
	s_addc_u32 s11, s29, 0
	s_mul_i32 s0, s78, 0xac00
	v_readlane_b32 s31, v252, 11
	s_add_u32 s12, s30, s0
	s_mul_i32 s86, s78, 0xac000
	v_readlane_b32 s36, v252, 12
	s_addc_u32 s13, s31, 0
	s_lshl_b64 s[0:1], s[86:87], 2
	v_readlane_b32 s44, v252, 20
	v_readlane_b32 s45, v252, 21
	s_add_u32 s18, s44, s0
	s_addc_u32 s19, s45, s1
	s_mul_i32 s2, s78, 0x56000
	v_readlane_b32 s3, v253, 53
	s_add_u32 s22, s3, s2
	v_readlane_b32 s2, v253, 54
	s_addc_u32 s23, s2, 0
	v_readlane_b32 s2, v253, 55
	s_add_u32 s64, s2, s0
	v_readlane_b32 s0, v253, 56
	s_addc_u32 s65, s0, s1
	v_readlane_b32 s0, v252, 0
	s_add_u32 s16, s10, 0x15800
	v_readlane_b32 s1, v252, 1
	s_addc_u32 s17, s11, 0
	v_readlane_b32 s2, v252, 2
	v_readlane_b32 s0, v254, 14
	v_readlane_b32 s3, v252, 3
	v_readlane_b32 s1, v254, 15
	s_add_u32 s44, s2, s0
	v_readlane_b32 s46, v252, 22
	s_addc_u32 s45, s3, s1
	v_readlane_b32 s26, v252, 6
	v_readlane_b32 s27, v252, 7
	v_readlane_b32 s47, v252, 23
	s_add_u32 s46, s44, 0x9100
	v_readlane_b32 s0, v253, 34
	s_addc_u32 s47, s45, 0
	s_mov_b32 s27, 11
	s_mov_b32 s28, 0
	s_mov_b32 s26, s0
	v_readlane_b32 s2, v255, 45
	v_readlane_b32 s3, v255, 46
	s_nop 0
	s_and_b64 s[2:3], s[2:3], exec
	s_cselect_b32 s2, 7, 10
	s_cmp_ge_u32 s0, 0xe0
	s_cselect_b32 s27, s2, 11
	s_waitcnt lgkmcnt(0)
	s_barrier
	v_readlane_b32 s25, v252, 5
	v_readlane_b32 s37, v252, 13
	v_readlane_b32 s38, v252, 14
	v_readlane_b32 s39, v252, 15
	v_readlane_b32 s40, v252, 16
	v_readlane_b32 s41, v252, 17
	v_readlane_b32 s42, v252, 18
	v_readlane_b32 s43, v252, 19
	v_readlane_b32 s48, v252, 24
	v_readlane_b32 s49, v252, 25
	v_readlane_b32 s50, v252, 26
	v_readlane_b32 s51, v252, 27
	v_readlane_b32 s1, v253, 35
	s_branch .LBB0_862

.LBB0_861:
	s_or_b64 exec, exec, s[0:1]
	v_mov_b32_e32 v0, s81
	s_waitcnt vmcnt(0) lgkmcnt(0)
	s_barrier
	ds_read_b32 v0, v0
	s_mov_b32 s27, 1
	s_mov_b32 s28, 11
	s_waitcnt lgkmcnt(0)
	s_barrier
	v_readfirstlane_b32 s26, v0
	s_cmp_lt_i32 s26, 22
	s_cbranch_scc1 .LBB0_862
	s_sub_i32 s26, s26, 22
	v_readlane_b32 s2, v255, 45
	v_readlane_b32 s3, v255, 46
	s_nop 0
	s_and_b64 s[2:3], s[2:3], exec
	s_cselect_b32 s2, 0x80, 32
	s_cmp_lt_i32 s26, s2
	s_cbranch_scc0 .LBB0_964
	s_lshr_b32 s2, s26, 5
	s_sub_i32 s28, 10, s2
	s_and_b32 s26, s26, 31
	s_addk_i32 s26, 0xe0

.LBB0_961:
	s_waitcnt vmcnt(0)
	v_readlane_b32 s90, v255, 59
	v_readlane_b32 s91, v255, 60
	v_readlane_b32 s53, v254, 0
	v_readlane_b32 s56, v254, 1
	s_mov_b32 s80, 0x20000
	v_readlane_b32 s81, v255, 62
	v_readlane_b32 s83, v255, 63
	s_mov_b32 s94, 0xf800000
	s_mov_b32 s95, 0x40000
	s_mov_b32 s96, 0x60000
	v_readlane_b32 s57, v254, 16
	s_barrier
	v_readlane_b32 s0, v253, 34
	s_nop 0
	s_cmp_ge_u32 s0, 0xe0
	s_cbranch_scc1 .LBB0_964
	s_and_saveexec_b64 s[0:1], s[90:91]
	s_cbranch_execz .LBB0_861

.LBB0_968:
	s_or_b64 exec, exec, s[2:3]
	v_readlane_b32 s2, v255, 45
	v_readlane_b32 s3, v255, 46
	s_and_b64 s[2:3], s[2:3], exec
	s_mov_b32 s2, 0x15600
	s_cselect_b32 s20, 0xf448, s2
	s_ashr_i32 s21, s18, 6
	v_and_b32_e32 v130, 63, v0
	s_mul_i32 s2, s21, 0x2500
	s_add_i32 s2, s2, 0
	v_bfe_u32 v133, v0, 4, 2
	v_lshlrev_b32_e32 v2, 2, v130
	v_and_b32_e32 v132, 60, v2
	v_or_b32_e32 v135, 4, v133
	v_or_b32_e32 v138, 8, v133
	v_or_b32_e32 v139, 12, v133
	v_or_b32_e32 v140, 16, v133
	v_or_b32_e32 v141, 20, v133
	v_or_b32_e32 v142, 24, v133
	v_or_b32_e32 v143, 28, v133
	v_or_b32_e32 v144, 32, v133
	v_or_b32_e32 v145, 36, v133
	v_or_b32_e32 v146, 40, v133
	v_or_b32_e32 v147, 44, v133
	v_or_b32_e32 v148, 48, v133
	v_or_b32_e32 v149, 52, v133
	v_or_b32_e32 v150, 56, v133
	v_or_b32_e32 v151, 60, v133
	v_add_u32_e32 v152, s2, v2
	v_mov_b32_e32 v2, s2
	s_movk_i32 s3, 0x90
	v_bfe_u32 v154, v0, 3, 3
	v_and_b32_e32 v0, 7, v0
	v_mad_u32_u24 v2, v132, s3, v2
	v_lshlrev_b32_e32 v3, 1, v133
	v_lshlrev_b32_e32 v4, 1, v135
	v_lshlrev_b32_e32 v5, 1, v138
	v_lshlrev_b32_e32 v6, 1, v139
	v_lshlrev_b32_e32 v7, 1, v140
	v_lshlrev_b32_e32 v8, 1, v141
	v_lshlrev_b32_e32 v9, 1, v142
	v_lshlrev_b32_e32 v10, 1, v143
	v_lshlrev_b32_e32 v11, 1, v144
	v_lshlrev_b32_e32 v12, 1, v145
	v_lshlrev_b32_e32 v13, 1, v146
	v_lshlrev_b32_e32 v14, 1, v147
	v_lshlrev_b32_e32 v15, 1, v148
	v_lshlrev_b32_e32 v16, 1, v149
	v_lshlrev_b32_e32 v17, 1, v150
	v_lshlrev_b32_e32 v18, 1, v151
	v_lshl_add_u32 v19, v0, 4, s2
	v_lshlrev_b32_e32 v134, 3, v0
	v_mul_u32_u24_e32 v0, 0x90, v154
	v_lshl_add_u32 v153, v133, 2, s2
	v_or_b32_e32 v155, 8, v154
	v_or_b32_e32 v156, 16, v154
	v_or_b32_e32 v157, 24, v154
	v_or_b32_e32 v158, 32, v154
	v_or_b32_e32 v159, 40, v154
	v_or_b32_e32 v160, 48, v154
	v_or_b32_e32 v161, 56, v154
	v_lshlrev_b32_e32 v5, 1, v134
	v_add_u32_e32 v3, v2, v3
	v_add_u32_e32 v4, v2, v4
	v_add_u32_e32 v162, v3, v5
	v_add_u32_e32 v163, v4, v5
	v_xor_b32_e32 v6, 16, v5
	v_add_u32_e32 v164, v3, v6
	v_add_u32_e32 v165, v4, v6
	v_xor_b32_e32 v6, 32, v5
	v_add_u32_e32 v166, v3, v6
	v_add_u32_e32 v167, v4, v6
	v_xor_b32_e32 v6, 48, v5
	v_add_u32_e32 v168, v3, v6
	v_add_u32_e32 v169, v4, v6
	v_xor_b32_e32 v6, 64, v5
	v_add_u32_e32 v180, v3, v6
	v_add_u32_e32 v181, v4, v6
	v_xor_b32_e32 v6, 0x50, v5
	v_add_u32_e32 v182, v3, v6
	v_add_u32_e32 v183, v4, v6
	v_xor_b32_e32 v6, 0x60, v5
	v_add_u32_e32 v184, v3, v6
	v_add_u32_e32 v185, v4, v6
	v_xor_b32_e32 v6, 0x70, v5
	v_add_u32_e32 v186, v3, v6
	v_add_u32_e32 v187, v4, v6
	v_add_u32_e32 v7, v19, v0
	v_sub_u32_e32 v7, v7, v5
	v_lshrrev_b32_e32 v8, 2, v154
	v_lshlrev_b32_e32 v8, 4, v8
	v_xor_b32_e32 v8, v8, v5
	v_add_u32_e32 v188, v7, v8
	v_xor_b32_e32 v9, 32, v8
	v_add_u32_e32 v244, v7, v9
	v_xor_b32_e32 v9, 64, v8
	v_add_u32_e32 v245, v7, v9
	v_xor_b32_e32 v9, 0x60, v8
	v_add_u32_e32 v246, v7, v9
	s_branch .LBB0_971

.LBB0_1000:
	ds_write_b32 v152, v190 offset:9216
	s_waitcnt lgkmcnt(0)
	ds_read_b32 v137, v153 offset:9216
	s_cmpk_eq_i32 s26, 0x2b00
	s_cselect_b64 s[2:3], -1, 0
	s_cmpk_eq_i32 s25, 0x2b00
	s_cselect_b64 s[30:31], -1, 0
	s_waitcnt lgkmcnt(0)
	v_mul_f32_e32 v170, v46, v137
	v_mul_f32_e32 v171, v47, v137
	v_cvt_pk_bf16_f32 v170, v170, v171
	v_mul_f32_e32 v171, v48, v137
	v_mul_f32_e32 v137, v49, v137
	v_cvt_pk_bf16_f32 v137, v171, v137
	ds_write_b16 v162, v170
	ds_write_b16_d16_hi v162, v170 offset:144
	ds_write_b16 v162, v137 offset:288
	ds_write_b16_d16_hi v162, v137 offset:432
	ds_read_b32 v137, v153 offset:9232
	s_or_b64 s[2:3], s[30:31], s[2:3]
	s_and_b64 s[2:3], s[2:3], exec
	s_cselect_b32 s2, 0x20002, 0
	s_cselect_b32 s3, 0xfffcfffc, -1
	s_waitcnt lgkmcnt(0)
	v_mul_f32_e32 v170, v42, v137
	v_mul_f32_e32 v171, v43, v137
	v_cvt_pk_bf16_f32 v170, v170, v171
	v_mul_f32_e32 v171, v44, v137
	v_mul_f32_e32 v137, v45, v137
	v_cvt_pk_bf16_f32 v137, v171, v137
	ds_write_b16 v163, v170
	ds_write_b16_d16_hi v163, v170 offset:144
	ds_write_b16 v163, v137 offset:288
	ds_write_b16_d16_hi v163, v137 offset:432
	ds_read_b32 v137, v153 offset:9248
	s_waitcnt lgkmcnt(0)
	v_mul_f32_e32 v170, v54, v137
	v_mul_f32_e32 v171, v55, v137
	v_cvt_pk_bf16_f32 v170, v170, v171
	v_mul_f32_e32 v171, v56, v137
	v_mul_f32_e32 v137, v57, v137
	v_cvt_pk_bf16_f32 v137, v171, v137
	ds_write_b16 v164, v170
	ds_write_b16_d16_hi v164, v170 offset:144
	ds_write_b16 v164, v137 offset:288
	ds_write_b16_d16_hi v164, v137 offset:432
	ds_read_b32 v137, v153 offset:9264
	s_waitcnt lgkmcnt(0)
	v_mul_f32_e32 v170, v50, v137
	v_mul_f32_e32 v171, v51, v137
	v_cvt_pk_bf16_f32 v170, v170, v171
	v_mul_f32_e32 v171, v52, v137
	v_mul_f32_e32 v137, v53, v137
	v_cvt_pk_bf16_f32 v137, v171, v137
	ds_write_b16 v165, v170
	ds_write_b16_d16_hi v165, v170 offset:144
	ds_write_b16 v165, v137 offset:288
	ds_write_b16_d16_hi v165, v137 offset:432
	ds_read_b32 v137, v153 offset:9280
	s_waitcnt lgkmcnt(0)
	v_mul_f32_e32 v170, v70, v137
	v_mul_f32_e32 v171, v71, v137
	v_cvt_pk_bf16_f32 v170, v170, v171
	v_mul_f32_e32 v171, v72, v137
	v_mul_f32_e32 v137, v73, v137
	v_cvt_pk_bf16_f32 v137, v171, v137
	ds_write_b16 v166, v170
	ds_write_b16_d16_hi v166, v170 offset:144
	ds_write_b16 v166, v137 offset:288
	ds_write_b16_d16_hi v166, v137 offset:432
	ds_read_b32 v137, v153 offset:9296
	s_waitcnt lgkmcnt(0)
	v_mul_f32_e32 v170, v66, v137
	v_mul_f32_e32 v171, v67, v137
	v_cvt_pk_bf16_f32 v170, v170, v171
	v_mul_f32_e32 v171, v68, v137
	v_mul_f32_e32 v137, v69, v137
	v_cvt_pk_bf16_f32 v137, v171, v137
	ds_write_b16 v167, v170
	ds_write_b16_d16_hi v167, v170 offset:144
	ds_write_b16 v167, v137 offset:288
	ds_write_b16_d16_hi v167, v137 offset:432
	ds_read_b32 v137, v153 offset:9312
	s_waitcnt lgkmcnt(0)
	v_mul_f32_e32 v170, v78, v137
	v_mul_f32_e32 v171, v79, v137
	v_cvt_pk_bf16_f32 v170, v170, v171
	v_mul_f32_e32 v171, v80, v137
	v_mul_f32_e32 v137, v81, v137
	v_cvt_pk_bf16_f32 v137, v171, v137
	ds_write_b16 v168, v170
	ds_write_b16_d16_hi v168, v170 offset:144
	ds_write_b16 v168, v137 offset:288
	ds_write_b16_d16_hi v168, v137 offset:432
	ds_read_b32 v137, v153 offset:9328
	s_waitcnt lgkmcnt(0)
	v_mul_f32_e32 v170, v74, v137
	v_mul_f32_e32 v171, v75, v137
	v_cvt_pk_bf16_f32 v170, v170, v171
	v_mul_f32_e32 v171, v76, v137
	v_mul_f32_e32 v137, v77, v137
	v_cvt_pk_bf16_f32 v137, v171, v137
	ds_write_b16 v169, v170
	ds_write_b16_d16_hi v169, v170 offset:144
	ds_write_b16 v169, v137 offset:288
	ds_write_b16_d16_hi v169, v137 offset:432
	ds_read_b32 v137, v153 offset:9344
	s_waitcnt lgkmcnt(0)
	v_mul_f32_e32 v170, v94, v137
	v_mul_f32_e32 v171, v95, v137
	v_cvt_pk_bf16_f32 v170, v170, v171
	v_mul_f32_e32 v171, v96, v137
	v_mul_f32_e32 v137, v97, v137
	v_cvt_pk_bf16_f32 v137, v171, v137
	ds_write_b16 v180, v170
	ds_write_b16_d16_hi v180, v170 offset:144
	ds_write_b16 v180, v137 offset:288
	ds_write_b16_d16_hi v180, v137 offset:432
	ds_read_b32 v137, v153 offset:9360
	s_waitcnt lgkmcnt(0)
	v_mul_f32_e32 v170, v90, v137
	v_mul_f32_e32 v171, v91, v137
	v_cvt_pk_bf16_f32 v170, v170, v171
	v_mul_f32_e32 v171, v92, v137
	v_mul_f32_e32 v137, v93, v137
	v_cvt_pk_bf16_f32 v137, v171, v137
	ds_write_b16 v181, v170
	ds_write_b16_d16_hi v181, v170 offset:144
	ds_write_b16 v181, v137 offset:288
	ds_write_b16_d16_hi v181, v137 offset:432
	ds_read_b32 v137, v153 offset:9376
	s_waitcnt lgkmcnt(0)
	v_mul_f32_e32 v170, v102, v137
	v_mul_f32_e32 v171, v103, v137
	v_cvt_pk_bf16_f32 v170, v170, v171
	v_mul_f32_e32 v171, v104, v137
	v_mul_f32_e32 v137, v105, v137
	v_cvt_pk_bf16_f32 v137, v171, v137
	ds_write_b16 v182, v170
	ds_write_b16_d16_hi v182, v170 offset:144
	ds_write_b16 v182, v137 offset:288
	ds_write_b16_d16_hi v182, v137 offset:432
	ds_read_b32 v137, v153 offset:9392
	s_waitcnt lgkmcnt(0)
	v_mul_f32_e32 v170, v98, v137
	v_mul_f32_e32 v171, v99, v137
	v_cvt_pk_bf16_f32 v170, v170, v171
	v_mul_f32_e32 v171, v100, v137
	v_mul_f32_e32 v137, v101, v137
	v_cvt_pk_bf16_f32 v137, v171, v137
	ds_write_b16 v183, v170
	ds_write_b16_d16_hi v183, v170 offset:144
	ds_write_b16 v183, v137 offset:288
	ds_write_b16_d16_hi v183, v137 offset:432
	ds_read_b32 v137, v153 offset:9408
	s_waitcnt lgkmcnt(0)
	v_mul_f32_e32 v170, v118, v137
	v_mul_f32_e32 v171, v119, v137
	v_cvt_pk_bf16_f32 v170, v170, v171
	v_mul_f32_e32 v171, v120, v137
	v_mul_f32_e32 v137, v121, v137
	v_cvt_pk_bf16_f32 v137, v171, v137
	ds_write_b16 v184, v170
	ds_write_b16_d16_hi v184, v170 offset:144
	ds_write_b16 v184, v137 offset:288
	ds_write_b16_d16_hi v184, v137 offset:432
	ds_read_b32 v137, v153 offset:9424
	s_waitcnt lgkmcnt(0)
	v_mul_f32_e32 v170, v114, v137
	v_mul_f32_e32 v171, v115, v137
	v_cvt_pk_bf16_f32 v170, v170, v171
	v_mul_f32_e32 v171, v116, v137
	v_mul_f32_e32 v137, v117, v137
	v_cvt_pk_bf16_f32 v137, v171, v137
	ds_write_b16 v185, v170
	ds_write_b16_d16_hi v185, v170 offset:144
	ds_write_b16 v185, v137 offset:288
	ds_write_b16_d16_hi v185, v137 offset:432
	ds_read_b32 v137, v153 offset:9440
	s_waitcnt lgkmcnt(0)
	v_mul_f32_e32 v170, v126, v137
	v_mul_f32_e32 v171, v127, v137
	v_cvt_pk_bf16_f32 v170, v170, v171
	v_mul_f32_e32 v171, v128, v137
	v_mul_f32_e32 v137, v129, v137
	v_cvt_pk_bf16_f32 v137, v171, v137
	ds_write_b16 v186, v170
	ds_write_b16_d16_hi v186, v170 offset:144
	ds_write_b16 v186, v137 offset:288
	ds_write_b16_d16_hi v186, v137 offset:432
	ds_read_b32 v137, v153 offset:9456
	s_waitcnt lgkmcnt(0)
	v_mul_f32_e32 v170, v122, v137
	v_mul_f32_e32 v171, v123, v137
	v_cvt_pk_bf16_f32 v170, v170, v171
	v_mul_f32_e32 v171, v124, v137
	v_mul_f32_e32 v137, v125, v137
	v_cvt_pk_bf16_f32 v137, v171, v137
	ds_write_b16 v187, v170
	ds_write_b16_d16_hi v187, v170 offset:144
	ds_write_b16 v187, v137 offset:288
	ds_write_b16_d16_hi v187, v137 offset:432
	s_waitcnt lgkmcnt(0)
	ds_read_b128 v[192:195], v188
	s_waitcnt lgkmcnt(0)
	v_add_u32_e32 v137, s2, v192
	v_and_b32_e32 v192, s3, v137
	v_add_u32_e32 v137, s2, v193
	v_and_b32_e32 v193, s3, v137
	v_add_u32_e32 v137, s2, v194
	v_and_b32_e32 v194, s3, v137
	v_add_u32_e32 v137, s2, v195
	v_and_b32_e32 v195, s3, v137
	v_add_u32_e32 v137, s28, v154
	v_mad_u64_u32 v[196:197], s[30:31], v137, s25, 0
	v_ashrrev_i32_e32 v170, 31, v137
	v_mov_b32_e32 v198, v197
	v_mad_u64_u32 v[198:199], s[30:31], v170, s25, v[198:199]
	v_mov_b32_e32 v197, v198
	v_lshl_add_u64 v[196:197], v[196:197], 1, s[8:9]
	v_lshl_add_u64 v[196:197], v[196:197], 0, v[0:1]
	global_store_dwordx4 v[196:197], v[192:195], off
	ds_read_b128 v[192:195], v244 offset:1152
	s_waitcnt lgkmcnt(0)
	v_add_u32_e32 v137, s2, v192
	v_and_b32_e32 v192, s3, v137
	v_add_u32_e32 v137, s2, v193
	v_and_b32_e32 v193, s3, v137
	v_add_u32_e32 v137, s2, v194
	v_and_b32_e32 v194, s3, v137
	v_add_u32_e32 v137, s2, v195
	v_and_b32_e32 v195, s3, v137
	v_add_u32_e32 v137, s28, v155
	v_mad_u64_u32 v[196:197], s[30:31], v137, s25, 0
	v_ashrrev_i32_e32 v170, 31, v137
	v_mov_b32_e32 v198, v197
	v_mad_u64_u32 v[198:199], s[30:31], v170, s25, v[198:199]
	v_mov_b32_e32 v197, v198
	v_lshl_add_u64 v[196:197], v[196:197], 1, s[8:9]
	v_lshl_add_u64 v[196:197], v[196:197], 0, v[0:1]
	global_store_dwordx4 v[196:197], v[192:195], off
	ds_read_b128 v[192:195], v245 offset:2304
	s_waitcnt lgkmcnt(0)
	v_add_u32_e32 v137, s2, v192
	v_and_b32_e32 v192, s3, v137
	v_add_u32_e32 v137, s2, v193
	v_and_b32_e32 v193, s3, v137
	v_add_u32_e32 v137, s2, v194
	v_and_b32_e32 v194, s3, v137
	v_add_u32_e32 v137, s2, v195
	v_and_b32_e32 v195, s3, v137
	v_add_u32_e32 v137, s28, v156
	v_mad_u64_u32 v[196:197], s[30:31], v137, s25, 0
	v_ashrrev_i32_e32 v170, 31, v137
	v_mov_b32_e32 v198, v197
	v_mad_u64_u32 v[198:199], s[30:31], v170, s25, v[198:199]
	v_mov_b32_e32 v197, v198
	v_lshl_add_u64 v[196:197], v[196:197], 1, s[8:9]
	v_lshl_add_u64 v[196:197], v[196:197], 0, v[0:1]
	global_store_dwordx4 v[196:197], v[192:195], off
	ds_read_b128 v[192:195], v246 offset:3456
	s_waitcnt lgkmcnt(0)
	v_add_u32_e32 v137, s2, v192
	v_and_b32_e32 v192, s3, v137
	v_add_u32_e32 v137, s2, v193
	v_and_b32_e32 v193, s3, v137
	v_add_u32_e32 v137, s2, v194
	v_and_b32_e32 v194, s3, v137
	v_add_u32_e32 v137, s2, v195
	v_and_b32_e32 v195, s3, v137
	v_add_u32_e32 v137, s28, v157
	v_mad_u64_u32 v[196:197], s[30:31], v137, s25, 0
	v_ashrrev_i32_e32 v170, 31, v137
	v_mov_b32_e32 v198, v197
	v_mad_u64_u32 v[198:199], s[30:31], v170, s25, v[198:199]
	v_mov_b32_e32 v197, v198
	v_lshl_add_u64 v[196:197], v[196:197], 1, s[8:9]
	v_lshl_add_u64 v[196:197], v[196:197], 0, v[0:1]
	global_store_dwordx4 v[196:197], v[192:195], off
	ds_read_b128 v[192:195], v188 offset:4608
	s_waitcnt lgkmcnt(0)
	v_add_u32_e32 v137, s2, v192
	v_and_b32_e32 v192, s3, v137
	v_add_u32_e32 v137, s2, v193
	v_and_b32_e32 v193, s3, v137
	v_add_u32_e32 v137, s2, v194
	v_and_b32_e32 v194, s3, v137
	v_add_u32_e32 v137, s2, v195
	v_and_b32_e32 v195, s3, v137
	v_add_u32_e32 v137, s28, v158
	v_mad_u64_u32 v[196:197], s[30:31], v137, s25, 0
	v_ashrrev_i32_e32 v170, 31, v137
	v_mov_b32_e32 v198, v197
	v_mad_u64_u32 v[198:199], s[30:31], v170, s25, v[198:199]
	v_mov_b32_e32 v197, v198
	v_lshl_add_u64 v[196:197], v[196:197], 1, s[8:9]
	v_lshl_add_u64 v[196:197], v[196:197], 0, v[0:1]
	global_store_dwordx4 v[196:197], v[192:195], off
	ds_read_b128 v[192:195], v244 offset:5760
	s_waitcnt lgkmcnt(0)
	v_add_u32_e32 v137, s2, v192
	v_and_b32_e32 v192, s3, v137
	v_add_u32_e32 v137, s2, v193
	v_and_b32_e32 v193, s3, v137
	v_add_u32_e32 v137, s2, v194
	v_and_b32_e32 v194, s3, v137
	v_add_u32_e32 v137, s2, v195
	v_and_b32_e32 v195, s3, v137
	v_add_u32_e32 v137, s28, v159
	v_mad_u64_u32 v[196:197], s[30:31], v137, s25, 0
	v_ashrrev_i32_e32 v170, 31, v137
	v_mov_b32_e32 v198, v197
	v_mad_u64_u32 v[198:199], s[30:31], v170, s25, v[198:199]
	v_mov_b32_e32 v197, v198
	v_lshl_add_u64 v[196:197], v[196:197], 1, s[8:9]
	v_lshl_add_u64 v[196:197], v[196:197], 0, v[0:1]
	global_store_dwordx4 v[196:197], v[192:195], off
	ds_read_b128 v[192:195], v245 offset:6912
	s_waitcnt lgkmcnt(0)
	v_add_u32_e32 v137, s2, v192
	v_and_b32_e32 v192, s3, v137
	v_add_u32_e32 v137, s2, v193
	v_and_b32_e32 v193, s3, v137
	v_add_u32_e32 v137, s2, v194
	v_and_b32_e32 v194, s3, v137
	v_add_u32_e32 v137, s2, v195
	v_and_b32_e32 v195, s3, v137
	v_add_u32_e32 v137, s28, v160
	v_mad_u64_u32 v[196:197], s[30:31], v137, s25, 0
	v_ashrrev_i32_e32 v170, 31, v137
	v_mov_b32_e32 v198, v197
	v_mad_u64_u32 v[198:199], s[30:31], v170, s25, v[198:199]
	v_mov_b32_e32 v197, v198
	v_lshl_add_u64 v[196:197], v[196:197], 1, s[8:9]
	v_lshl_add_u64 v[196:197], v[196:197], 0, v[0:1]
	global_store_dwordx4 v[196:197], v[192:195], off
	ds_read_b128 v[192:195], v246 offset:8064
	s_waitcnt lgkmcnt(0)
	v_add_u32_e32 v137, s2, v192
	v_and_b32_e32 v192, s3, v137
	v_add_u32_e32 v137, s2, v193
	v_and_b32_e32 v193, s3, v137
	v_add_u32_e32 v137, s2, v194
	v_and_b32_e32 v194, s3, v137
	v_add_u32_e32 v137, s2, v195
	v_and_b32_e32 v195, s3, v137
	v_add_u32_e32 v137, s28, v161
	v_mad_u64_u32 v[196:197], s[2:3], v137, s25, 0
	v_ashrrev_i32_e32 v170, 31, v137
	v_mov_b32_e32 v198, v197
	v_mad_u64_u32 v[198:199], s[2:3], v170, s25, v[198:199]
	v_mov_b32_e32 v197, v198
	v_lshl_add_u64 v[196:197], v[196:197], 1, s[8:9]
	v_lshl_add_u64 v[196:197], v[196:197], 0, v[0:1]
	global_store_dwordx4 v[196:197], v[192:195], off
	s_waitcnt lgkmcnt(0)

.LBB0_1022:
	s_waitcnt vmcnt(16)
	ds_write_b32 v152, v191 offset:9216
	s_waitcnt lgkmcnt(0)
	ds_read_b32 v0, v153 offset:9216
	s_cmpk_eq_i32 s24, 0x2b00
	s_cselect_b64 s[2:3], -1, 0
	s_cmpk_eq_i32 s23, 0x2b00
	s_cselect_b64 s[18:19], -1, 0
	s_waitcnt vmcnt(15) lgkmcnt(0)
	v_mul_f32_e32 v137, v2, v0
	v_mul_f32_e32 v170, v3, v0
	v_cvt_pk_bf16_f32 v137, v137, v170
	v_mul_f32_e32 v170, v4, v0
	v_mul_f32_e32 v0, v5, v0
	v_cvt_pk_bf16_f32 v0, v170, v0
	ds_write_b16 v162, v137
	ds_write_b16_d16_hi v162, v137 offset:144
	ds_write_b16 v162, v0 offset:288
	ds_write_b16_d16_hi v162, v0 offset:432
	ds_read_b32 v0, v153 offset:9232
	s_or_b64 s[2:3], s[18:19], s[2:3]
	s_and_b64 s[2:3], s[2:3], exec
	s_cselect_b32 s2, 0x20002, 0
	s_cselect_b32 s3, 0xfffcfffc, -1
	s_waitcnt vmcnt(14) lgkmcnt(0)
	v_mul_f32_e32 v137, v6, v0
	v_mul_f32_e32 v170, v7, v0
	v_cvt_pk_bf16_f32 v137, v137, v170
	v_mul_f32_e32 v170, v8, v0
	v_mul_f32_e32 v0, v9, v0
	v_cvt_pk_bf16_f32 v0, v170, v0
	ds_write_b16 v163, v137
	ds_write_b16_d16_hi v163, v137 offset:144
	ds_write_b16 v163, v0 offset:288
	ds_write_b16_d16_hi v163, v0 offset:432
	ds_read_b32 v0, v153 offset:9248
	s_andn2_b64 vcc, exec, s[34:35]
	s_waitcnt vmcnt(13) lgkmcnt(0)
	v_mul_f32_e32 v137, v10, v0
	v_mul_f32_e32 v170, v11, v0
	v_cvt_pk_bf16_f32 v137, v137, v170
	v_mul_f32_e32 v170, v12, v0
	v_mul_f32_e32 v0, v13, v0
	v_cvt_pk_bf16_f32 v0, v170, v0
	ds_write_b16 v164, v137
	ds_write_b16_d16_hi v164, v137 offset:144
	ds_write_b16 v164, v0 offset:288
	ds_write_b16_d16_hi v164, v0 offset:432
	ds_read_b32 v0, v153 offset:9264
	s_waitcnt vmcnt(12) lgkmcnt(0)
	v_mul_f32_e32 v137, v14, v0
	v_mul_f32_e32 v170, v15, v0
	v_cvt_pk_bf16_f32 v137, v137, v170
	v_mul_f32_e32 v170, v16, v0
	v_mul_f32_e32 v0, v17, v0
	v_cvt_pk_bf16_f32 v0, v170, v0
	ds_write_b16 v165, v137
	ds_write_b16_d16_hi v165, v137 offset:144
	ds_write_b16 v165, v0 offset:288
	ds_write_b16_d16_hi v165, v0 offset:432
	ds_read_b32 v0, v153 offset:9280
	s_waitcnt vmcnt(11) lgkmcnt(0)
	v_mul_f32_e32 v137, v18, v0
	v_mul_f32_e32 v170, v19, v0
	v_cvt_pk_bf16_f32 v137, v137, v170
	v_mul_f32_e32 v170, v20, v0
	v_mul_f32_e32 v0, v21, v0
	v_cvt_pk_bf16_f32 v0, v170, v0
	ds_write_b16 v166, v137
	ds_write_b16_d16_hi v166, v137 offset:144
	ds_write_b16 v166, v0 offset:288
	ds_write_b16_d16_hi v166, v0 offset:432
	ds_read_b32 v0, v153 offset:9296
	s_waitcnt vmcnt(10) lgkmcnt(0)
	v_mul_f32_e32 v137, v22, v0
	v_mul_f32_e32 v170, v23, v0
	v_cvt_pk_bf16_f32 v137, v137, v170
	v_mul_f32_e32 v170, v24, v0
	v_mul_f32_e32 v0, v25, v0
	v_cvt_pk_bf16_f32 v0, v170, v0
	ds_write_b16 v167, v137
	ds_write_b16_d16_hi v167, v137 offset:144
	ds_write_b16 v167, v0 offset:288
	ds_write_b16_d16_hi v167, v0 offset:432
	ds_read_b32 v0, v153 offset:9312
	s_waitcnt vmcnt(9) lgkmcnt(0)
	v_mul_f32_e32 v137, v26, v0
	v_mul_f32_e32 v170, v27, v0
	v_cvt_pk_bf16_f32 v137, v137, v170
	v_mul_f32_e32 v170, v28, v0
	v_mul_f32_e32 v0, v29, v0
	v_cvt_pk_bf16_f32 v0, v170, v0
	ds_write_b16 v168, v137
	ds_write_b16_d16_hi v168, v137 offset:144
	ds_write_b16 v168, v0 offset:288
	ds_write_b16_d16_hi v168, v0 offset:432
	ds_read_b32 v0, v153 offset:9328
	s_waitcnt vmcnt(8) lgkmcnt(0)
	v_mul_f32_e32 v137, v30, v0
	v_mul_f32_e32 v170, v31, v0
	v_cvt_pk_bf16_f32 v137, v137, v170
	v_mul_f32_e32 v170, v32, v0
	v_mul_f32_e32 v0, v33, v0
	v_cvt_pk_bf16_f32 v0, v170, v0
	ds_write_b16 v169, v137
	ds_write_b16_d16_hi v169, v137 offset:144
	ds_write_b16 v169, v0 offset:288
	ds_write_b16_d16_hi v169, v0 offset:432
	ds_read_b32 v0, v153 offset:9344
	s_waitcnt vmcnt(7) lgkmcnt(0)
	v_mul_f32_e32 v137, v34, v0
	v_mul_f32_e32 v170, v35, v0
	v_cvt_pk_bf16_f32 v137, v137, v170
	v_mul_f32_e32 v170, v36, v0
	v_mul_f32_e32 v0, v37, v0
	v_cvt_pk_bf16_f32 v0, v170, v0
	ds_write_b16 v180, v137
	ds_write_b16_d16_hi v180, v137 offset:144
	ds_write_b16 v180, v0 offset:288
	ds_write_b16_d16_hi v180, v0 offset:432
	ds_read_b32 v0, v153 offset:9360
	s_waitcnt vmcnt(6) lgkmcnt(0)
	v_mul_f32_e32 v137, v38, v0
	v_mul_f32_e32 v170, v39, v0
	v_cvt_pk_bf16_f32 v137, v137, v170
	v_mul_f32_e32 v170, v40, v0
	v_mul_f32_e32 v0, v41, v0
	v_cvt_pk_bf16_f32 v0, v170, v0
	ds_write_b16 v181, v137
	ds_write_b16_d16_hi v181, v137 offset:144
	ds_write_b16 v181, v0 offset:288
	ds_write_b16_d16_hi v181, v0 offset:432
	ds_read_b32 v0, v153 offset:9376
	s_waitcnt vmcnt(5) lgkmcnt(0)
	v_mul_f32_e32 v137, v58, v0
	v_mul_f32_e32 v170, v59, v0
	v_cvt_pk_bf16_f32 v137, v137, v170
	v_mul_f32_e32 v170, v60, v0
	v_mul_f32_e32 v0, v61, v0
	v_cvt_pk_bf16_f32 v0, v170, v0
	ds_write_b16 v182, v137
	ds_write_b16_d16_hi v182, v137 offset:144
	ds_write_b16 v182, v0 offset:288
	ds_write_b16_d16_hi v182, v0 offset:432
	ds_read_b32 v0, v153 offset:9392
	s_waitcnt vmcnt(4) lgkmcnt(0)
	v_mul_f32_e32 v137, v62, v0
	v_mul_f32_e32 v170, v63, v0
	v_cvt_pk_bf16_f32 v137, v137, v170
	v_mul_f32_e32 v170, v64, v0
	v_mul_f32_e32 v0, v65, v0
	v_cvt_pk_bf16_f32 v0, v170, v0
	ds_write_b16 v183, v137
	ds_write_b16_d16_hi v183, v137 offset:144
	ds_write_b16 v183, v0 offset:288
	ds_write_b16_d16_hi v183, v0 offset:432
	ds_read_b32 v0, v153 offset:9408
	s_waitcnt vmcnt(3) lgkmcnt(0)
	v_mul_f32_e32 v137, v82, v0
	v_mul_f32_e32 v170, v83, v0
	v_cvt_pk_bf16_f32 v137, v137, v170
	v_mul_f32_e32 v170, v84, v0
	v_mul_f32_e32 v0, v85, v0
	v_cvt_pk_bf16_f32 v0, v170, v0
	ds_write_b16 v184, v137
	ds_write_b16_d16_hi v184, v137 offset:144
	ds_write_b16 v184, v0 offset:288
	ds_write_b16_d16_hi v184, v0 offset:432
	ds_read_b32 v0, v153 offset:9424
	s_waitcnt vmcnt(2) lgkmcnt(0)
	v_mul_f32_e32 v137, v86, v0
	v_mul_f32_e32 v170, v87, v0
	v_cvt_pk_bf16_f32 v137, v137, v170
	v_mul_f32_e32 v170, v88, v0
	v_mul_f32_e32 v0, v89, v0
	v_cvt_pk_bf16_f32 v0, v170, v0
	ds_write_b16 v185, v137
	ds_write_b16_d16_hi v185, v137 offset:144
	ds_write_b16 v185, v0 offset:288
	ds_write_b16_d16_hi v185, v0 offset:432
	ds_read_b32 v0, v153 offset:9440
	s_waitcnt vmcnt(1) lgkmcnt(0)
	v_mul_f32_e32 v137, v106, v0
	v_mul_f32_e32 v170, v107, v0
	v_cvt_pk_bf16_f32 v137, v137, v170
	v_mul_f32_e32 v170, v108, v0
	v_mul_f32_e32 v0, v109, v0
	v_cvt_pk_bf16_f32 v0, v170, v0
	ds_write_b16 v186, v137
	ds_write_b16_d16_hi v186, v137 offset:144
	ds_write_b16 v186, v0 offset:288
	ds_write_b16_d16_hi v186, v0 offset:432
	ds_read_b32 v0, v153 offset:9456
	s_waitcnt vmcnt(0) lgkmcnt(0)
	v_mul_f32_e32 v137, v110, v0
	v_mul_f32_e32 v170, v111, v0
	v_cvt_pk_bf16_f32 v137, v137, v170
	v_mul_f32_e32 v170, v112, v0
	v_mul_f32_e32 v0, v113, v0
	v_cvt_pk_bf16_f32 v0, v170, v0
	ds_write_b16 v187, v137
	ds_write_b16_d16_hi v187, v137 offset:144
	ds_write_b16 v187, v0 offset:288
	ds_write_b16_d16_hi v187, v0 offset:432
	s_waitcnt lgkmcnt(0)
	ds_read_b128 v[192:195], v188
	s_waitcnt lgkmcnt(0)
	v_add_u32_e32 v0, s2, v192
	v_and_b32_e32 v192, s3, v0
	v_add_u32_e32 v0, s2, v193
	v_and_b32_e32 v193, s3, v0
	v_add_u32_e32 v0, s2, v194
	v_and_b32_e32 v194, s3, v0
	v_add_u32_e32 v0, s2, v195
	v_and_b32_e32 v195, s3, v0
	v_add_u32_e32 v0, s27, v154
	v_mad_u64_u32 v[196:197], s[18:19], v0, s23, 0
	v_ashrrev_i32_e32 v137, 31, v0
	v_mov_b32_e32 v0, v197
	v_mad_u64_u32 v[198:199], s[18:19], v137, s23, v[0:1]
	v_mov_b32_e32 v197, v198
	v_lshl_add_u64 v[196:197], v[196:197], 1, s[6:7]
	v_lshlrev_b32_e32 v0, 1, v134
	v_lshl_add_u64 v[196:197], v[196:197], 0, v[0:1]
	global_store_dwordx4 v[196:197], v[192:195], off
	ds_read_b128 v[192:195], v244 offset:1152
	s_waitcnt lgkmcnt(0)
	v_add_u32_e32 v137, s2, v192
	v_and_b32_e32 v192, s3, v137
	v_add_u32_e32 v137, s2, v193
	v_and_b32_e32 v193, s3, v137
	v_add_u32_e32 v137, s2, v194
	v_and_b32_e32 v194, s3, v137
	v_add_u32_e32 v137, s2, v195
	v_and_b32_e32 v195, s3, v137
	v_add_u32_e32 v137, s27, v155
	v_mad_u64_u32 v[196:197], s[18:19], v137, s23, 0
	v_ashrrev_i32_e32 v170, 31, v137
	v_mov_b32_e32 v198, v197
	v_mad_u64_u32 v[198:199], s[18:19], v170, s23, v[198:199]
	v_mov_b32_e32 v197, v198
	v_lshl_add_u64 v[196:197], v[196:197], 1, s[6:7]
	v_lshl_add_u64 v[196:197], v[196:197], 0, v[0:1]
	global_store_dwordx4 v[196:197], v[192:195], off
	ds_read_b128 v[192:195], v245 offset:2304
	s_waitcnt lgkmcnt(0)
	v_add_u32_e32 v137, s2, v192
	v_and_b32_e32 v192, s3, v137
	v_add_u32_e32 v137, s2, v193
	v_and_b32_e32 v193, s3, v137
	v_add_u32_e32 v137, s2, v194
	v_and_b32_e32 v194, s3, v137
	v_add_u32_e32 v137, s2, v195
	v_and_b32_e32 v195, s3, v137
	v_add_u32_e32 v137, s27, v156
	v_mad_u64_u32 v[196:197], s[18:19], v137, s23, 0
	v_ashrrev_i32_e32 v170, 31, v137
	v_mov_b32_e32 v198, v197
	v_mad_u64_u32 v[198:199], s[18:19], v170, s23, v[198:199]
	v_mov_b32_e32 v197, v198
	v_lshl_add_u64 v[196:197], v[196:197], 1, s[6:7]
	v_lshl_add_u64 v[196:197], v[196:197], 0, v[0:1]
	global_store_dwordx4 v[196:197], v[192:195], off
	ds_read_b128 v[192:195], v246 offset:3456
	s_waitcnt lgkmcnt(0)
	v_add_u32_e32 v137, s2, v192
	v_and_b32_e32 v192, s3, v137
	v_add_u32_e32 v137, s2, v193
	v_and_b32_e32 v193, s3, v137
	v_add_u32_e32 v137, s2, v194
	v_and_b32_e32 v194, s3, v137
	v_add_u32_e32 v137, s2, v195
	v_and_b32_e32 v195, s3, v137
	v_add_u32_e32 v137, s27, v157
	v_mad_u64_u32 v[196:197], s[18:19], v137, s23, 0
	v_ashrrev_i32_e32 v170, 31, v137
	v_mov_b32_e32 v198, v197
	v_mad_u64_u32 v[198:199], s[18:19], v170, s23, v[198:199]
	v_mov_b32_e32 v197, v198
	v_lshl_add_u64 v[196:197], v[196:197], 1, s[6:7]
	v_lshl_add_u64 v[196:197], v[196:197], 0, v[0:1]
	global_store_dwordx4 v[196:197], v[192:195], off
	ds_read_b128 v[192:195], v188 offset:4608
	s_waitcnt lgkmcnt(0)
	v_add_u32_e32 v137, s2, v192
	v_and_b32_e32 v192, s3, v137
	v_add_u32_e32 v137, s2, v193
	v_and_b32_e32 v193, s3, v137
	v_add_u32_e32 v137, s2, v194
	v_and_b32_e32 v194, s3, v137
	v_add_u32_e32 v137, s2, v195
	v_and_b32_e32 v195, s3, v137
	v_add_u32_e32 v137, s27, v158
	v_mad_u64_u32 v[196:197], s[18:19], v137, s23, 0
	v_ashrrev_i32_e32 v170, 31, v137
	v_mov_b32_e32 v198, v197
	v_mad_u64_u32 v[198:199], s[18:19], v170, s23, v[198:199]
	v_mov_b32_e32 v197, v198
	v_lshl_add_u64 v[196:197], v[196:197], 1, s[6:7]
	v_lshl_add_u64 v[196:197], v[196:197], 0, v[0:1]
	global_store_dwordx4 v[196:197], v[192:195], off
	ds_read_b128 v[192:195], v244 offset:5760
	s_waitcnt lgkmcnt(0)
	v_add_u32_e32 v137, s2, v192
	v_and_b32_e32 v192, s3, v137
	v_add_u32_e32 v137, s2, v193
	v_and_b32_e32 v193, s3, v137
	v_add_u32_e32 v137, s2, v194
	v_and_b32_e32 v194, s3, v137
	v_add_u32_e32 v137, s2, v195
	v_and_b32_e32 v195, s3, v137
	v_add_u32_e32 v137, s27, v159
	v_mad_u64_u32 v[196:197], s[18:19], v137, s23, 0
	v_ashrrev_i32_e32 v170, 31, v137
	v_mov_b32_e32 v198, v197
	v_mad_u64_u32 v[198:199], s[18:19], v170, s23, v[198:199]
	v_mov_b32_e32 v197, v198
	v_lshl_add_u64 v[196:197], v[196:197], 1, s[6:7]
	v_lshl_add_u64 v[196:197], v[196:197], 0, v[0:1]
	global_store_dwordx4 v[196:197], v[192:195], off
	ds_read_b128 v[192:195], v245 offset:6912
	s_waitcnt lgkmcnt(0)
	v_add_u32_e32 v137, s2, v192
	v_and_b32_e32 v192, s3, v137
	v_add_u32_e32 v137, s2, v193
	v_and_b32_e32 v193, s3, v137
	v_add_u32_e32 v137, s2, v194
	v_and_b32_e32 v194, s3, v137
	v_add_u32_e32 v137, s2, v195
	v_and_b32_e32 v195, s3, v137
	v_add_u32_e32 v137, s27, v160
	v_mad_u64_u32 v[196:197], s[18:19], v137, s23, 0
	v_ashrrev_i32_e32 v170, 31, v137
	v_mov_b32_e32 v198, v197
	v_mad_u64_u32 v[198:199], s[18:19], v170, s23, v[198:199]
	v_mov_b32_e32 v197, v198
	v_lshl_add_u64 v[196:197], v[196:197], 1, s[6:7]
	v_lshl_add_u64 v[196:197], v[196:197], 0, v[0:1]
	global_store_dwordx4 v[196:197], v[192:195], off
	ds_read_b128 v[192:195], v246 offset:8064
	s_mov_b64 s[18:19], -1
	s_waitcnt lgkmcnt(0)
	v_add_u32_e32 v137, s2, v192
	v_and_b32_e32 v192, s3, v137
	v_add_u32_e32 v137, s2, v193
	v_and_b32_e32 v193, s3, v137
	v_add_u32_e32 v137, s2, v194
	v_and_b32_e32 v194, s3, v137
	v_add_u32_e32 v137, s2, v195
	v_and_b32_e32 v195, s3, v137
	v_add_u32_e32 v137, s27, v161
	v_mad_u64_u32 v[196:197], s[2:3], v137, s23, 0
	v_ashrrev_i32_e32 v170, 31, v137
	v_mov_b32_e32 v198, v197
	v_mad_u64_u32 v[198:199], s[2:3], v170, s23, v[198:199]
	v_mov_b32_e32 v197, v198
	v_lshl_add_u64 v[196:197], v[196:197], 1, s[6:7]
	v_lshl_add_u64 v[196:197], v[196:197], 0, v[0:1]
	global_store_dwordx4 v[196:197], v[192:195], off
	s_waitcnt lgkmcnt(0)
	s_cbranch_vccnz .LBB0_1001
	s_add_i32 s31, s30, 16
	s_cmp_ge_i32 s31, s22
	s_cselect_b64 s[18:19], -1, 0
	s_and_b64 vcc, exec, s[18:19]
	s_cbranch_vccnz .LBB0_1000
	s_cmp_gt_i32 s30, 0xaaef
	s_cselect_b64 s[64:65], -1, 0
	s_and_b64 s[2:3], s[64:65], exec
	s_cselect_b32 s29, 0xffff5500, 0
	s_cselect_b32 s2, 0x15600000, 0
	s_add_i32 s29, s29, s31
	s_add_u32 s6, s53, s2
	s_addc_u32 s7, s56, 0
	s_cmpk_gt_i32 s29, 0x19ff
	s_mov_b64 s[72:73], -1
	s_cbranch_scc0 .LBB0_1037
	s_cmpk_gt_u32 s29, 0x29ff
	s_cbranch_scc0 .LBB0_1034
	s_and_b64 s[2:3], s[64:65], exec
	s_cselect_b32 s33, 0x2b00000, 0
	s_cmpk_gt_u32 s29, 0x54ff
	s_cbranch_scc0 .LBB0_1031
	s_mov_b64 s[66:67], -1
	s_cmpk_gt_u32 s29, 0x7fff
	s_mov_b64 s[70:71], -1
	s_cbranch_scc0 .LBB0_1029
	v_readlane_b32 s36, v252, 4
	s_add_i32 s27, s29, 0xffff8000
	s_lshl_b32 s2, s33, 2
	v_readlane_b32 s38, v252, 6
	v_readlane_b32 s39, v252, 7
	s_add_u32 s2, s38, s2
	s_addc_u32 s3, s39, 0
	s_add_u32 s34, s6, 0x10000000
	v_readlane_b32 s37, v252, 5
	v_readlane_b32 s40, v252, 8
	v_readlane_b32 s41, v252, 9
	v_readlane_b32 s42, v252, 10
	v_readlane_b32 s43, v252, 11
	s_addc_u32 s35, s7, 0
	s_mov_b64 s[70:71], 0
